# hidden buffer placed XCD-aligned inside the scan region, norm3 output moved to the dead PB region; P9|P10 barrier XCD-local (all barriers after P8 local)
# baseline (speedup 1.0000x reference)
; __device__ __forceinline__ unsigned pk2(float lo, float hi) { const f32x2c v = {lo, hi}; const bf16x2c b = __builtin_convertvector(v, bf16x2c); return __builtin_bit_cast(unsigned, b); }
; __device__ __forceinline__ float silu_f(float x) { return x * fast_sigmoid(x); }
;     __device__ __forceinline__ void operator()(const f32x4 (&acc)[2][2][4][2], const pg8::Unit& u, int wr, int wc, int fr, int fq) const {
;         const int row0 = u.pm * 256 + wr * 64 + fr, col0 = u.pn * 128 + wc * 32 + 8 * fq;
; #pragma unroll
;         for (int ai = 0; ai < 2; ++ai)
; #pragma unroll
;             for (int m = 0; m < 4; ++m) {
;                 bf16_t* rowp = O + (size_t)(row0 + ai * 128 + m * 16) * ldc + col0;
;                 const f32x4 a0 = acc[ai][0][m][0], a1 = acc[ai][0][m][1], b0 = acc[ai][1][m][0], b1 = acc[ai][1][m][1];
;                 u32x4 w;
;                 w.x = pk2(silu_f(a0[0]) * b0[0], silu_f(a0[1]) * b0[1]); w.y = pk2(silu_f(a0[2]) * b0[2], silu_f(a0[3]) * b0[3]);
;                 w.z = pk2(silu_f(a1[0]) * b1[0], silu_f(a1[1]) * b1[1]); w.w = pk2(silu_f(a1[2]) * b1[2], silu_f(a1[3]) * b1[3]);
;                 *(u32x4*)rowp = w;
;             }
.LBB0_153:
	v_mul_f32_e32 v155, 0xbfb8aa3b, v124
	v_exp_f32_e32 v155, v155
	v_mul_f32_e32 v158, 0xbfb8aa3b, v125
	v_exp_f32_e32 v159, v158
	v_lshl_add_u32 v154, s28, 8, v148
	v_add_f32_e32 v155, 1.0, v155
	v_rcp_f32_e32 v158, v155
	v_add_f32_e32 v155, 1.0, v159
	v_mul_f32_e32 v159, 0xbfb8aa3b, v126
	v_exp_f32_e32 v160, v159
	v_mul_f32_e32 v159, 0xbfb8aa3b, v127
	v_exp_f32_e32 v161, v159
	v_rcp_f32_e32 v159, v155
	v_add_f32_e32 v155, 1.0, v160
	v_rcp_f32_e32 v160, v155
	v_add_f32_e32 v155, 1.0, v161
	v_rcp_f32_e32 v161, v155
	v_pk_mul_f32 v[124:125], v[124:125], v[158:159]
	v_lshl_add_u32 v144, s71, 7, v150
	v_pk_mul_f32 v[120:121], v[124:125], v[120:121]
	v_pk_mul_f32 v[124:125], v[126:127], v[160:161]
	v_cvt_pk_bf16_f32 v120, v120, v121
	v_mul_f32_e32 v121, 0xbfb8aa3b, v116
	v_pk_mul_f32 v[122:123], v[124:125], v[122:123]
	v_exp_f32_e32 v124, v121
	v_mul_f32_e32 v121, 0xbfb8aa3b, v117
	v_exp_f32_e32 v125, v121
	v_cvt_pk_bf16_f32 v121, v122, v123
	v_add_f32_e32 v122, 1.0, v124
	v_mul_f32_e32 v124, 0xbfb8aa3b, v118
	v_add_f32_e32 v123, 1.0, v125
	v_mul_f32_e32 v125, 0xbfb8aa3b, v119
	v_exp_f32_e32 v124, v124
	v_exp_f32_e32 v125, v125
	v_rcp_f32_e32 v122, v122
	v_rcp_f32_e32 v123, v123
	v_add_f32_e32 v124, 1.0, v124
	v_add_f32_e32 v125, 1.0, v125
	v_rcp_f32_e32 v124, v124
	v_rcp_f32_e32 v125, v125
	v_pk_mul_f32 v[116:117], v[116:117], v[122:123]
	v_ashrrev_i32_e32 v145, 31, v144
	v_pk_mul_f32 v[112:113], v[116:117], v[112:113]
	v_mul_f32_e32 v116, 0xbfb8aa3b, v110
	v_cvt_pk_bf16_f32 v122, v112, v113
	v_pk_mul_f32 v[112:113], v[118:119], v[124:125]
	v_mul_f32_e32 v117, 0xbfb8aa3b, v111
	v_pk_mul_f32 v[112:113], v[112:113], v[114:115]
	v_mul_f32_e32 v114, 0xbfb8aa3b, v108
	v_mul_f32_e32 v115, 0xbfb8aa3b, v109
	v_exp_f32_e32 v114, v114
	v_exp_f32_e32 v115, v115
	v_exp_f32_e32 v116, v116
	v_exp_f32_e32 v117, v117
	v_add_f32_e32 v114, 1.0, v114
	v_add_f32_e32 v115, 1.0, v115
	v_rcp_f32_e32 v114, v114
	v_rcp_f32_e32 v115, v115
	v_add_f32_e32 v116, 1.0, v116
	v_add_f32_e32 v117, 1.0, v117
	v_rcp_f32_e32 v116, v116
	v_rcp_f32_e32 v117, v117
	v_pk_mul_f32 v[108:109], v[108:109], v[114:115]
	s_cselect_b32 s98, 1, 0
	s_lshr_b32 s99, s28, 1
	s_and_b32 s100, s99, 7
	s_lshl_b32 s100, s100, 1
	s_bfe_u32 s101, s99, 0x10003
	s_or_b32 s100, s100, s101
	s_and_b32 s101, s99, 0x30
	s_or_b32 s100, s100, s101
	s_mul_i32 s100, s100, 0x300000
	s_mul_i32 s99, s99, 0x2c0000
	s_add_u32 s100, s100, 0xd000000
	s_sub_u32 s100, s100, s99
	s_add_u32 s100, s96, s100
	s_addc_u32 s101, s97, 0
	s_cmp_lg_u32 s98, 0
	v_mov_b64_e32 v[146:147], s[100:101]
	v_pk_mul_f32 v[104:105], v[108:109], v[104:105]
	v_pk_mul_f32 v[108:109], v[110:111], v[116:117]
	v_cvt_pk_bf16_f32 v104, v104, v105
	v_mul_f32_e32 v105, 0xbfb8aa3b, v100
	v_pk_mul_f32 v[106:107], v[108:109], v[106:107]
	v_exp_f32_e32 v108, v105
	v_mul_f32_e32 v105, 0xbfb8aa3b, v101
	v_exp_f32_e32 v109, v105
	v_cvt_pk_bf16_f32 v105, v106, v107
	v_add_f32_e32 v106, 1.0, v108
	v_mul_f32_e32 v108, 0xbfb8aa3b, v102
	v_add_f32_e32 v107, 1.0, v109
	v_mul_f32_e32 v109, 0xbfb8aa3b, v103
	v_exp_f32_e32 v108, v108
	v_exp_f32_e32 v109, v109
	v_rcp_f32_e32 v106, v106
	v_rcp_f32_e32 v107, v107
	v_add_f32_e32 v108, 1.0, v108
	v_add_f32_e32 v109, 1.0, v109
	v_rcp_f32_e32 v108, v108
	v_rcp_f32_e32 v109, v109
	v_pk_mul_f32 v[100:101], v[100:101], v[106:107]
	v_cvt_pk_bf16_f32 v123, v112, v113
	v_pk_mul_f32 v[96:97], v[100:101], v[96:97]
	v_mul_f32_e32 v100, 0xbfb8aa3b, v94
	v_cvt_pk_bf16_f32 v106, v96, v97
	v_pk_mul_f32 v[96:97], v[102:103], v[108:109]
	v_mul_f32_e32 v101, 0xbfb8aa3b, v95
	v_pk_mul_f32 v[96:97], v[96:97], v[98:99]
	v_mul_f32_e32 v98, 0xbfb8aa3b, v92
	v_mul_f32_e32 v99, 0xbfb8aa3b, v93
	v_exp_f32_e32 v98, v98
	v_exp_f32_e32 v99, v99
	v_exp_f32_e32 v100, v100
	v_exp_f32_e32 v101, v101
	v_add_f32_e32 v98, 1.0, v98
	v_add_f32_e32 v99, 1.0, v99
	v_rcp_f32_e32 v98, v98
	v_rcp_f32_e32 v99, v99
	v_add_f32_e32 v100, 1.0, v100
	v_add_f32_e32 v101, 1.0, v101
	v_rcp_f32_e32 v100, v100
	v_rcp_f32_e32 v101, v101
	v_pk_mul_f32 v[92:93], v[92:93], v[98:99]
	v_or_b32_e32 v112, 16, v154
	v_pk_mul_f32 v[88:89], v[92:93], v[88:89]
	v_pk_mul_f32 v[92:93], v[94:95], v[100:101]
	v_cvt_pk_bf16_f32 v88, v88, v89
	v_mul_f32_e32 v89, 0xbfb8aa3b, v84
	v_pk_mul_f32 v[90:91], v[92:93], v[90:91]
	v_exp_f32_e32 v92, v89
	v_mul_f32_e32 v89, 0xbfb8aa3b, v85
	v_exp_f32_e32 v93, v89
	v_cvt_pk_bf16_f32 v89, v90, v91
	v_add_f32_e32 v90, 1.0, v92
	v_mul_f32_e32 v92, 0xbfb8aa3b, v86
	v_add_f32_e32 v91, 1.0, v93
	v_mul_f32_e32 v93, 0xbfb8aa3b, v87
	v_exp_f32_e32 v92, v92
	v_exp_f32_e32 v93, v93
	v_rcp_f32_e32 v90, v90
	v_rcp_f32_e32 v91, v91
	v_add_f32_e32 v92, 1.0, v92
	v_add_f32_e32 v93, 1.0, v93
	v_rcp_f32_e32 v92, v92
	v_rcp_f32_e32 v93, v93
	v_pk_mul_f32 v[84:85], v[84:85], v[90:91]
	v_cvt_pk_bf16_f32 v107, v96, v97
	v_pk_mul_f32 v[80:81], v[84:85], v[80:81]
	v_mul_f32_e32 v84, 0xbfb8aa3b, v78
	v_cvt_pk_bf16_f32 v90, v80, v81
	v_pk_mul_f32 v[80:81], v[86:87], v[92:93]
	v_mul_f32_e32 v85, 0xbfb8aa3b, v79
	v_pk_mul_f32 v[80:81], v[80:81], v[82:83]
	v_mul_f32_e32 v82, 0xbfb8aa3b, v76
	v_mul_f32_e32 v83, 0xbfb8aa3b, v77
	v_exp_f32_e32 v82, v82
	v_exp_f32_e32 v83, v83
	v_exp_f32_e32 v84, v84
	v_exp_f32_e32 v85, v85
	v_add_f32_e32 v82, 1.0, v82
	v_add_f32_e32 v83, 1.0, v83
	v_rcp_f32_e32 v82, v82
	v_rcp_f32_e32 v83, v83
	v_add_f32_e32 v84, 1.0, v84
	v_add_f32_e32 v85, 1.0, v85
	v_rcp_f32_e32 v84, v84
	v_rcp_f32_e32 v85, v85
	v_pk_mul_f32 v[76:77], v[76:77], v[82:83]
	v_or_b32_e32 v96, 32, v154
	v_pk_mul_f32 v[72:73], v[76:77], v[72:73]
	v_pk_mul_f32 v[76:77], v[78:79], v[84:85]
	v_cvt_pk_bf16_f32 v72, v72, v73
	v_mul_f32_e32 v73, 0xbfb8aa3b, v68
; __device__ __forceinline__ unsigned pk2(float lo, float hi) { const f32x2c v = {lo, hi}; const bf16x2c b = __builtin_convertvector(v, bf16x2c); return __builtin_bit_cast(unsigned, b); }
; __device__ __forceinline__ float silu_f(float x) { return x * fast_sigmoid(x); }
;     __device__ __forceinline__ void operator()(const f32x4 (&acc)[2][2][4][2], const pg8::Unit& u, int wr, int wc, int fr, int fq) const {
;         const int row0 = u.pm * 256 + wr * 64 + fr, col0 = u.pn * 128 + wc * 32 + 8 * fq;
; #pragma unroll
;         for (int ai = 0; ai < 2; ++ai)
; #pragma unroll
;             for (int m = 0; m < 4; ++m) {
;                 bf16_t* rowp = O + (size_t)(row0 + ai * 128 + m * 16) * ldc + col0;
;                 const f32x4 a0 = acc[ai][0][m][0], a1 = acc[ai][0][m][1], b0 = acc[ai][1][m][0], b1 = acc[ai][1][m][1];
;                 u32x4 w;
;                 w.x = pk2(silu_f(a0[0]) * b0[0], silu_f(a0[1]) * b0[1]); w.y = pk2(silu_f(a0[2]) * b0[2], silu_f(a0[3]) * b0[3]);
;                 w.z = pk2(silu_f(a1[0]) * b1[0], silu_f(a1[1]) * b1[1]); w.w = pk2(silu_f(a1[2]) * b1[2], silu_f(a1[3]) * b1[3]);
;                 *(u32x4*)rowp = w;
;             }
	v_pk_mul_f32 v[74:75], v[76:77], v[74:75]
	v_exp_f32_e32 v76, v73
	v_mul_f32_e32 v73, 0xbfb8aa3b, v69
	v_exp_f32_e32 v77, v73
	v_cvt_pk_bf16_f32 v73, v74, v75
	v_add_f32_e32 v74, 1.0, v76
	v_mul_f32_e32 v76, 0xbfb8aa3b, v70
	v_add_f32_e32 v75, 1.0, v77
	v_mul_f32_e32 v77, 0xbfb8aa3b, v71
	v_exp_f32_e32 v76, v76
	v_exp_f32_e32 v77, v77
	v_rcp_f32_e32 v74, v74
	v_rcp_f32_e32 v75, v75
	v_add_f32_e32 v76, 1.0, v76
	v_add_f32_e32 v77, 1.0, v77
	v_rcp_f32_e32 v76, v76
	v_rcp_f32_e32 v77, v77
	v_pk_mul_f32 v[68:69], v[68:69], v[74:75]
	v_cvt_pk_bf16_f32 v91, v80, v81
	v_pk_mul_f32 v[64:65], v[68:69], v[64:65]
	v_mul_f32_e32 v68, 0xbfb8aa3b, v62
	v_cvt_pk_bf16_f32 v74, v64, v65
	v_pk_mul_f32 v[64:65], v[70:71], v[76:77]
	v_mul_f32_e32 v69, 0xbfb8aa3b, v63
	v_pk_mul_f32 v[64:65], v[64:65], v[66:67]
	v_mul_f32_e32 v66, 0xbfb8aa3b, v60
	v_mul_f32_e32 v67, 0xbfb8aa3b, v61
	v_exp_f32_e32 v66, v66
	v_exp_f32_e32 v67, v67
	v_exp_f32_e32 v68, v68
	v_exp_f32_e32 v69, v69
	v_add_f32_e32 v66, 1.0, v66
	v_add_f32_e32 v67, 1.0, v67
	v_rcp_f32_e32 v66, v66
	v_rcp_f32_e32 v67, v67
	v_add_f32_e32 v68, 1.0, v68
	v_add_f32_e32 v69, 1.0, v69
	v_rcp_f32_e32 v68, v68
	v_rcp_f32_e32 v69, v69
	v_pk_mul_f32 v[60:61], v[60:61], v[66:67]
	v_or_b32_e32 v80, 48, v154
	v_pk_mul_f32 v[56:57], v[60:61], v[56:57]
	v_pk_mul_f32 v[60:61], v[62:63], v[68:69]
	v_cvt_pk_bf16_f32 v56, v56, v57
	v_mul_f32_e32 v57, 0xbfb8aa3b, v52
	v_pk_mul_f32 v[58:59], v[60:61], v[58:59]
	v_exp_f32_e32 v60, v57
	v_mul_f32_e32 v57, 0xbfb8aa3b, v53
	v_exp_f32_e32 v61, v57
	v_cvt_pk_bf16_f32 v57, v58, v59
	v_add_f32_e32 v58, 1.0, v60
	v_mul_f32_e32 v60, 0xbfb8aa3b, v54
	v_add_f32_e32 v59, 1.0, v61
	v_mul_f32_e32 v61, 0xbfb8aa3b, v55
	v_exp_f32_e32 v60, v60
	v_exp_f32_e32 v61, v61
	v_rcp_f32_e32 v58, v58
	v_rcp_f32_e32 v59, v59
	v_add_f32_e32 v60, 1.0, v60
	v_add_f32_e32 v61, 1.0, v61
	v_rcp_f32_e32 v60, v60
	v_rcp_f32_e32 v61, v61
	v_pk_mul_f32 v[52:53], v[52:53], v[58:59]
	v_cvt_pk_bf16_f32 v75, v64, v65
	v_pk_mul_f32 v[48:49], v[52:53], v[48:49]
	v_mul_f32_e32 v52, 0xbfb8aa3b, v46
	v_cvt_pk_bf16_f32 v58, v48, v49
	v_pk_mul_f32 v[48:49], v[54:55], v[60:61]
	v_mul_f32_e32 v53, 0xbfb8aa3b, v47
	v_pk_mul_f32 v[48:49], v[48:49], v[50:51]
	v_mul_f32_e32 v50, 0xbfb8aa3b, v44
	v_mul_f32_e32 v51, 0xbfb8aa3b, v45
	v_exp_f32_e32 v50, v50
	v_exp_f32_e32 v51, v51
	v_exp_f32_e32 v52, v52
	v_exp_f32_e32 v53, v53
	v_add_f32_e32 v50, 1.0, v50
	v_add_f32_e32 v51, 1.0, v51
	v_rcp_f32_e32 v50, v50
	v_rcp_f32_e32 v51, v51
	v_add_f32_e32 v52, 1.0, v52
	v_add_f32_e32 v53, 1.0, v53
	v_rcp_f32_e32 v52, v52
	v_rcp_f32_e32 v53, v53
	v_pk_mul_f32 v[44:45], v[44:45], v[50:51]
	v_add_u32_e32 v64, 0x80, v154
	v_pk_mul_f32 v[40:41], v[44:45], v[40:41]
	v_pk_mul_f32 v[44:45], v[46:47], v[52:53]
	v_cvt_pk_bf16_f32 v40, v40, v41
	v_mul_f32_e32 v41, 0xbfb8aa3b, v36
	v_pk_mul_f32 v[42:43], v[44:45], v[42:43]
	v_exp_f32_e32 v44, v41
	v_mul_f32_e32 v41, 0xbfb8aa3b, v37
	v_exp_f32_e32 v45, v41
	v_cvt_pk_bf16_f32 v41, v42, v43
	v_add_f32_e32 v42, 1.0, v44
	v_mul_f32_e32 v44, 0xbfb8aa3b, v38
	v_add_f32_e32 v43, 1.0, v45
	v_mul_f32_e32 v45, 0xbfb8aa3b, v39
	v_exp_f32_e32 v44, v44
	v_exp_f32_e32 v45, v45
	v_rcp_f32_e32 v42, v42
	v_rcp_f32_e32 v43, v43
	v_add_f32_e32 v44, 1.0, v44
	v_add_f32_e32 v45, 1.0, v45
	v_rcp_f32_e32 v44, v44
	v_rcp_f32_e32 v45, v45
	v_pk_mul_f32 v[36:37], v[36:37], v[42:43]
	v_cvt_pk_bf16_f32 v59, v48, v49
	v_pk_mul_f32 v[32:33], v[36:37], v[32:33]
	v_mul_f32_e32 v36, 0xbfb8aa3b, v30
	v_cvt_pk_bf16_f32 v42, v32, v33
	v_pk_mul_f32 v[32:33], v[38:39], v[44:45]
	v_mul_f32_e32 v37, 0xbfb8aa3b, v31
	v_pk_mul_f32 v[32:33], v[32:33], v[34:35]
	v_mul_f32_e32 v34, 0xbfb8aa3b, v28
	v_mul_f32_e32 v35, 0xbfb8aa3b, v29
	v_exp_f32_e32 v34, v34
	v_exp_f32_e32 v35, v35
	v_exp_f32_e32 v36, v36
	v_exp_f32_e32 v37, v37
	v_add_f32_e32 v34, 1.0, v34
	v_add_f32_e32 v35, 1.0, v35
	v_rcp_f32_e32 v34, v34
	v_rcp_f32_e32 v35, v35
	v_add_f32_e32 v36, 1.0, v36
; __device__ __forceinline__ unsigned pk2(float lo, float hi) { const f32x2c v = {lo, hi}; const bf16x2c b = __builtin_convertvector(v, bf16x2c); return __builtin_bit_cast(unsigned, b); }
; __device__ __forceinline__ float silu_f(float x) { return x * fast_sigmoid(x); }
; template <class Epi, class Sched, bool ALIGN_EPI = false, bool SP2 = false>
; __device__ __forceinline__ void gemm_phase(PG8_LAS unsigned char* lds, const Gemm g, const Sched& S, const Epi& E, const int wid) {
;     ...
;         if constexpr (!Epi::AFTER_DRAIN) { E(acc, cur, wr, wc, fr, fq); S.done(cur); }
;         if (!has_next) break;
;     __device__ __forceinline__ void operator()(const f32x4 (&acc)[2][2][4][2], const pg8::Unit& u, int wr, int wc, int fr, int fq) const {
;         const int row0 = u.pm * 256 + wr * 64 + fr, col0 = u.pn * 128 + wc * 32 + 8 * fq;
; #pragma unroll
;         for (int ai = 0; ai < 2; ++ai)
; #pragma unroll
;             for (int m = 0; m < 4; ++m) {
;                 bf16_t* rowp = O + (size_t)(row0 + ai * 128 + m * 16) * ldc + col0;
;                 const f32x4 a0 = acc[ai][0][m][0], a1 = acc[ai][0][m][1], b0 = acc[ai][1][m][0], b1 = acc[ai][1][m][1];
;                 u32x4 w;
;                 w.x = pk2(silu_f(a0[0]) * b0[0], silu_f(a0[1]) * b0[1]); w.y = pk2(silu_f(a0[2]) * b0[2], silu_f(a0[3]) * b0[3]);
;                 w.z = pk2(silu_f(a1[0]) * b1[0], silu_f(a1[1]) * b1[1]); w.w = pk2(silu_f(a1[2]) * b1[2], silu_f(a1[3]) * b1[3]);
;                 *(u32x4*)rowp = w;
;             }
	v_add_f32_e32 v37, 1.0, v37
	v_rcp_f32_e32 v36, v36
	v_rcp_f32_e32 v37, v37
	v_pk_mul_f32 v[28:29], v[28:29], v[34:35]
	v_add_u32_e32 v48, 0x90, v154
	v_pk_mul_f32 v[24:25], v[28:29], v[24:25]
	v_pk_mul_f32 v[28:29], v[30:31], v[36:37]
	v_cvt_pk_bf16_f32 v24, v24, v25
	v_mul_f32_e32 v25, 0xbfb8aa3b, v20
	v_pk_mul_f32 v[26:27], v[28:29], v[26:27]
	v_exp_f32_e32 v28, v25
	v_mul_f32_e32 v25, 0xbfb8aa3b, v21
	v_exp_f32_e32 v29, v25
	v_cvt_pk_bf16_f32 v25, v26, v27
	v_add_f32_e32 v26, 1.0, v28
	v_mul_f32_e32 v28, 0xbfb8aa3b, v22
	v_add_f32_e32 v27, 1.0, v29
	v_mul_f32_e32 v29, 0xbfb8aa3b, v23
	v_exp_f32_e32 v28, v28
	v_exp_f32_e32 v29, v29
	v_rcp_f32_e32 v26, v26
	v_rcp_f32_e32 v27, v27
	v_add_f32_e32 v28, 1.0, v28
	v_add_f32_e32 v29, 1.0, v29
	v_rcp_f32_e32 v28, v28
	v_rcp_f32_e32 v29, v29
	v_pk_mul_f32 v[20:21], v[20:21], v[26:27]
	v_cvt_pk_bf16_f32 v43, v32, v33
	v_pk_mul_f32 v[16:17], v[20:21], v[16:17]
	v_mul_f32_e32 v20, 0xbfb8aa3b, v14
	v_cvt_pk_bf16_f32 v26, v16, v17
	v_pk_mul_f32 v[16:17], v[22:23], v[28:29]
	v_mul_f32_e32 v21, 0xbfb8aa3b, v15
	v_pk_mul_f32 v[16:17], v[16:17], v[18:19]
	v_mul_f32_e32 v18, 0xbfb8aa3b, v12
	v_mul_f32_e32 v19, 0xbfb8aa3b, v13
	v_exp_f32_e32 v18, v18
	v_exp_f32_e32 v19, v19
	v_exp_f32_e32 v20, v20
	v_exp_f32_e32 v21, v21
	v_add_f32_e32 v18, 1.0, v18
	v_add_f32_e32 v19, 1.0, v19
	v_rcp_f32_e32 v18, v18
	v_rcp_f32_e32 v19, v19
	v_add_f32_e32 v20, 1.0, v20
	v_add_f32_e32 v21, 1.0, v21
	v_rcp_f32_e32 v20, v20
	v_rcp_f32_e32 v21, v21
	v_pk_mul_f32 v[12:13], v[12:13], v[18:19]
	v_add_u32_e32 v32, 0xa0, v154
	v_pk_mul_f32 v[8:9], v[12:13], v[8:9]
	v_pk_mul_f32 v[12:13], v[14:15], v[20:21]
	v_cvt_pk_bf16_f32 v8, v8, v9
	v_mul_f32_e32 v9, 0xbfb8aa3b, v4
	v_pk_mul_f32 v[10:11], v[12:13], v[10:11]
	v_exp_f32_e32 v12, v9
	v_mul_f32_e32 v9, 0xbfb8aa3b, v5
	v_exp_f32_e32 v13, v9
	v_cvt_pk_bf16_f32 v9, v10, v11
	v_add_f32_e32 v10, 1.0, v12
	v_mul_f32_e32 v12, 0xbfb8aa3b, v6
	v_add_f32_e32 v11, 1.0, v13
	v_mul_f32_e32 v13, 0xbfb8aa3b, v7
	v_exp_f32_e32 v12, v12
	v_exp_f32_e32 v13, v13
	v_rcp_f32_e32 v10, v10
	v_rcp_f32_e32 v11, v11
	v_add_f32_e32 v12, 1.0, v12
	v_add_f32_e32 v13, 1.0, v13
	v_rcp_f32_e32 v12, v12
	v_rcp_f32_e32 v13, v13
	v_pk_mul_f32 v[4:5], v[4:5], v[10:11]
	v_cvt_pk_bf16_f32 v27, v16, v17
	v_pk_mul_f32 v[0:1], v[4:5], v[0:1]
	v_add_u32_e32 v16, 0xb0, v154
	v_cvt_pk_bf16_f32 v10, v0, v1
	v_pk_mul_f32 v[0:1], v[6:7], v[12:13]
	v_mad_i64_i32 v[156:157], s[30:31], v154, s70, v[146:147]
	v_lshlrev_b64 v[144:145], 1, v[144:145]
	v_mad_i64_i32 v[112:113], s[30:31], v112, s70, v[146:147]
	v_mad_i64_i32 v[96:97], s[30:31], v96, s70, v[146:147]
	v_mad_i64_i32 v[80:81], s[30:31], v80, s70, v[146:147]
	v_mad_i64_i32 v[64:65], s[30:31], v64, s70, v[146:147]
	v_mad_i64_i32 v[48:49], s[30:31], v48, s70, v[146:147]
	v_mad_i64_i32 v[32:33], s[30:31], v32, s70, v[146:147]
	v_mad_i64_i32 v[16:17], s[30:31], v16, s70, v[146:147]
	v_pk_mul_f32 v[0:1], v[0:1], v[2:3]
	v_lshl_add_u64 v[156:157], v[156:157], 0, v[144:145]
	v_lshl_add_u64 v[112:113], v[112:113], 0, v[144:145]
	v_lshl_add_u64 v[96:97], v[96:97], 0, v[144:145]
	v_lshl_add_u64 v[80:81], v[80:81], 0, v[144:145]
	v_lshl_add_u64 v[64:65], v[64:65], 0, v[144:145]
	v_lshl_add_u64 v[48:49], v[48:49], 0, v[144:145]
	v_lshl_add_u64 v[32:33], v[32:33], 0, v[144:145]
	v_lshl_add_u64 v[16:17], v[16:17], 0, v[144:145]
	v_cvt_pk_bf16_f32 v11, v0, v1
	s_andn2_b64 vcc, exec, s[4:5]
	s_mov_b64 s[4:5], -1
	global_store_dwordx4 v[156:157], v[120:123], off
	global_store_dwordx4 v[112:113], v[104:107], off
	global_store_dwordx4 v[96:97], v[88:91], off
	global_store_dwordx4 v[80:81], v[72:75], off
	global_store_dwordx4 v[64:65], v[56:59], off
	global_store_dwordx4 v[48:49], v[40:43], off
	global_store_dwordx4 v[32:33], v[24:27], off
	global_store_dwordx4 v[16:17], v[8:11], off
	s_cbranch_vccnz .LBB0_146
	s_andn2_b64 vcc, exec, s[6:7]
	s_cbranch_vccnz .LBB0_145
	s_barrier
	s_branch .LBB0_145

; #define PG8_STAGE(bufoff, gbase, voff) do { _Pragma("unroll") for (int _i = 0; _i < 2; ++_i) \
;         __builtin_amdgcn_global_load_lds((const unsigned*)((const char*)(gbase) + (voff)[_i]), (PG8_LAS unsigned*)(lds + (bufoff) + ldsw + _i * 8192), 16, 0, 0); } while (0)
; #define PG8_WAIT_V(n) asm volatile("s_waitcnt vmcnt(" #n ")" ::: "memory")
; #define PG8_BAR __builtin_amdgcn_s_barrier()
; template <class Epi, class Sched, bool ALIGN_EPI = false, bool SP2 = false>
; __device__ __forceinline__ void gemm_phase(PG8_LAS unsigned char* lds, const Gemm g, const Sched& S, const Epi& E, const int wid) {
;     ...
;     for (int i = 0; i < 2; ++i) { int R, C; stage_rc(tid * 16 + i * 8192, R, C); const int Rb = Epi::PERM ? ((R & ~31) + perm32(R & 31)) : R;
;         voffA[i] = (unsigned)(R * K + C) * 2u; voffB[i] = (unsigned)(Rb * K + C) * 2u; }
;     const size_t kstep = (size_t)(BK * 2);
;     const size_t hstep = (size_t)HALF * K * 2;
;     const size_t tstep = 2 * hstep;
;     const unsigned ldsw = (unsigned)wid * 1024u;
;     const int aoff = lds_byte(wr * 64 + fr, fq * 8), boff = lds_byte(wc * 32 + fr, fq * 8);
;     ...
;     const char* cA = (const char*)g.A + (size_t)cur.pm * tstep; const char* cB = (const char*)g.Bt + (size_t)cur.pn * tstep;
;     S.a_ready(cur);
;     if constexpr (SP2) {
;         PG8_STAGE(PG8_SB(0, 0), cB, voffB); PG8_STAGE(PG8_SB(0, 1), cB + hstep, voffB); PG8_STAGE(PG8_SA(0, 0), cA, voffA); PG8_STAGE(PG8_SA(0, 1), cA + hstep, voffA);
;         if (wr == 1) PG8_BAR;
;         PG8_WAIT_V(2); PG8_BAR;
;         PG8_STAGE(PG8_SB(1, 0), cB + kstep, voffB); PG8_STAGE(PG8_SA(1, 0), cA + kstep, voffA); PG8_STAGE(PG8_SB(1, 1), cB + hstep + kstep, voffB);
.LBB0_216:
	v_lshl_add_u32 v0, v13, 4, s33
	v_ashrrev_i32_e32 v1, 31, v0
	v_lshrrev_b32_e32 v1, 22, v1
	v_add_u32_e32 v1, v0, v1
	v_ashrrev_i32_e32 v8, 10, v1
	v_mul_i32_i24_e32 v1, 0x400, v8
	v_sub_u32_e32 v1, v0, v1
	v_lshrrev_b32_e32 v2, 4, v1
	v_bitop3_b32 v1, v2, v1, 32 bitop3:0x6c
	v_ashrrev_i32_e32 v3, 31, v1
	v_lshrrev_b32_e32 v3, 26, v3
	v_lshlrev_b32_e32 v2, 3, v8
	v_add_u32_e32 v3, v1, v3
	v_and_b32_e32 v2, -16, v2
	v_ashrrev_i32_e32 v10, 6, v3
	v_and_b32_e32 v3, 0xc0, v3
	v_add_u32_e32 v2, v10, v2
	v_lshlrev_b32_e32 v4, 5, v8
	v_sub_u32_e32 v1, v1, v3
	v_mov_b32_e32 v3, 1
	s_ashr_i32 s5, s7, 3
	v_and_b32_e32 v9, 32, v4
	v_ashrrev_i16_sdwa v1, v3, sext(v1) dst_sel:DWORD dst_unused:UNUSED_PAD src0_sel:DWORD src1_sel:BYTE_0
	v_lshlrev_b32_e32 v4, 1, v2
	v_lshrrev_b32_e32 v5, 2, v2
	v_and_b32_e32 v6, 3, v10
	s_mov_b32 s7, 0xffffe0
	v_bfe_i32 v11, v1, 0, 16
	v_and_b32_e32 v4, 24, v4
	v_and_b32_e32 v5, 4, v5
	v_and_or_b32 v6, v2, s7, v6
	s_movk_i32 s4, 0xb00
	v_add_u32_e32 v1, v9, v11
	v_or3_b32 v4, v6, v5, v4
	v_mul_lo_u32 v2, v2, s4
	v_add_lshl_u32 v128, v1, v2, 1
	v_mul_u32_u24_e32 v2, 0xb00, v4
	v_add_u32_e32 v0, 0x2000, v0
	v_add_lshl_u32 v130, v2, v1, 1
	v_ashrrev_i32_e32 v1, 31, v0
	v_lshrrev_b32_e32 v1, 22, v1
	v_add_u32_e32 v1, v0, v1
	v_ashrrev_i32_e32 v12, 10, v1
	v_mul_i32_i24_e32 v1, 0x400, v12
	v_sub_u32_e32 v0, v0, v1
	v_lshrrev_b32_e32 v1, 4, v0
	v_bitop3_b32 v0, v1, v0, 32 bitop3:0x6c
	s_add_u32 s35, s92, 0xc00000
	v_ashrrev_i32_e32 v2, 31, v0
	s_addc_u32 s38, s93, 0
	v_lshrrev_b32_e32 v2, 26, v2
	s_add_i32 s5, s6, s5
	v_lshlrev_b32_e32 v1, 3, v12
	v_add_u32_e32 v2, v0, v2
	s_ashr_i32 s6, s5, 31
	v_and_b32_e32 v1, -16, v1
	v_ashrrev_i32_e32 v14, 6, v2
	v_lshlrev_b32_e32 v4, 5, v12
	s_lshr_b32 s6, s6, 28
	v_add_u32_e32 v1, v14, v1
	v_and_b32_e32 v15, 32, v4
	v_and_b32_e32 v4, 3, v14
	s_add_i32 s6, s5, s6
	v_and_or_b32 v4, v1, s7, v4
	s_ashr_i32 s7, s6, 4
	s_and_b32 s6, s6, -16
	s_sub_i32 s6, s5, s6
	s_bfe_i32 s5, s6, 0x80000
	s_bfe_u32 s5, s5, 0x2000d
	s_add_i32 s10, s6, s5
	v_and_b32_e32 v2, 0xffc0, v2
	s_bfe_i32 s5, s10, 0x80000
	s_and_b32 s10, s10, 0xfc
	v_sub_u32_e32 v0, v0, v2
	s_sub_i32 s6, s6, s10
	v_lshrrev_b16_e32 v2, 7, v0
	s_lshl_b32 s7, s7, 2
	s_sext_i32_i16 s11, s5
	s_sext_i32_i8 s6, s6
	v_and_b32_e32 v2, 1, v2
	s_add_i32 s70, s7, s6
	s_ashr_i32 s6, s11, 2
	v_add_u16_e32 v0, v0, v2
	s_lshr_b32 s5, s11, 2
	s_mul_hi_i32 s7, s6, 0x160000
	s_mul_i32 s6, s6, 0x160000
	v_ashrrev_i16_sdwa v0, v3, sext(v0) dst_sel:DWORD dst_unused:UNUSED_PAD src0_sel:DWORD src1_sel:BYTE_0
	v_lshlrev_b32_e32 v2, 1, v1
	v_lshrrev_b32_e32 v3, 2, v1
	s_add_u32 s26, s35, s6
	v_bfe_i32 v16, v0, 0, 16
	v_and_b32_e32 v2, 24, v2
	v_and_b32_e32 v3, 4, v3
	s_addc_u32 s27, s38, s7
	s_add_i32 s39, s33, 0
	v_add_u32_e32 v0, v15, v16
	v_or3_b32 v2, v4, v3, v2
	v_mul_lo_u32 v1, v1, s4
	s_add_i32 m0, s39, 0x10000
	v_add_lshl_u32 v132, v0, v1, 1
	v_mul_u32_u24_e32 v1, 0xb00, v2
	global_load_lds_dwordx4 v130, s[26:27]
	s_add_i32 m0, s39, 0x12000
	v_add_lshl_u32 v134, v1, v0, 1
	s_add_u32 s6, s26, 0xb0000
	global_load_lds_dwordx4 v134, s[26:27]
	s_addc_u32 s7, s27, 0
	s_add_i32 m0, s39, 0x14000
	s_mul_i32 s16, s70, 0x160000
	global_load_lds_dwordx4 v130, s[6:7]
	s_add_i32 m0, s39, 0x16000
	s_mul_hi_i32 s10, s70, 0x160000
	s_add_u32 s24, s96, s16
	s_addc_u32 s25, s97, s10
	s_lshr_b32 s98, s70, 1
	s_and_b32 s99, s98, 7
	s_lshl_b32 s99, s99, 1
	s_bfe_u32 s100, s98, 0x10003
	s_or_b32 s99, s99, s100
	s_and_b32 s100, s98, 0x30
	s_or_b32 s99, s99, s100
	s_mul_i32 s99, s99, 0x300000
	s_mul_i32 s98, s98, 0x2c0000
	s_add_u32 s99, s99, 0xd000000
	s_sub_u32 s99, s99, s98
	s_add_u32 s24, s24, s99
	s_addc_u32 s25, s25, 0
	s_add_i32 s40, s39, 0x2000
	global_load_lds_dwordx4 v134, s[6:7]
	s_mov_b32 m0, s39
	s_add_u32 s6, s24, 0xb0000
	global_load_lds_dwordx4 v128, s[24:25]
	s_mov_b32 m0, s40
	s_addc_u32 s7, s25, 0
	s_add_i32 s41, s39, 0x4000
	global_load_lds_dwordx4 v132, s[24:25]
	s_mov_b32 m0, s41
	s_add_i32 s42, s39, 0x6000
	global_load_lds_dwordx4 v128, s[6:7]
	s_mov_b32 m0, s42
	v_mov_b32_e32 v131, 0
	global_load_lds_dwordx4 v132, s[6:7]
	v_readlane_b32 s6, v244, 18
	v_mov_b32_e32 v135, v131
	v_mov_b32_e32 v129, v131
	v_mov_b32_e32 v133, v131
	s_cmp_eq_u32 s6, 1
	s_mov_b32 s43, 0
	v_lshl_add_u64 v[4:5], s[26:27], 0, v[130:131]
	v_lshl_add_u64 v[2:3], s[26:27], 0, v[134:135]
	v_lshl_add_u64 v[0:1], s[24:25], 0, v[128:129]
	s_cselect_b64 s[10:11], -1, 0
	s_cmp_lg_u32 s6, 1
	v_lshl_add_u64 v[6:7], s[24:25], 0, v[132:133]
	s_cbranch_scc1 .LBB0_218
	s_barrier

; template <class Epi, class Sched, bool ALIGN_EPI = false, bool SP2 = false>
; __device__ __forceinline__ void gemm_phase(PG8_LAS unsigned char* lds, const Gemm g, const Sched& S, const Epi& E, const int wid) {
;     ...
;         const bool has_next = S.next(ui + 1, nxt);
;         const char* nA = has_next ? (const char*)g.A + (size_t)nxt.pm * tstep : cA; const char* nB = has_next ? (const char*)g.Bt + (size_t)nxt.pn * tstep : cB;
;         for (int t = 0; t < nt; t += 2) {
;             const bool last = (t == nt - 2);
;             const char* a1 = cA + (size_t)(t + 1) * kstep;
;             const char* a2 = last ? nA : cA + (size_t)(t + 2) * kstep; const char* b2 = last ? nB : cB + (size_t)(t + 2) * kstep;
;             const char* a3 = a2 + kstep; const char* b3 = b2 + kstep;
;             if (last && has_next) S.a_ready(nxt);
.LBB0_227:
	s_nop 0
	v_cndmask_b32_e64 v0, 0, 1, s[4:5]
	v_cmp_ne_u32_e64 s[6:7], 1, v0
	s_andn2_b64 vcc, exec, s[4:5]
	s_mov_b64 s[4:5], s[24:25]
	s_cbranch_vccnz .LBB0_229
	s_mul_i32 s4, s69, 0x160000
	s_mul_hi_i32 s5, s69, 0x160000
	s_add_u32 s4, s96, s4
	s_addc_u32 s5, s97, s5
	s_lshr_b32 s98, s69, 1
	s_and_b32 s99, s98, 7
	s_lshl_b32 s99, s99, 1
	s_bfe_u32 s100, s98, 0x10003
	s_or_b32 s99, s99, s100
	s_and_b32 s100, s98, 0x30
	s_or_b32 s99, s99, s100
	s_mul_i32 s99, s99, 0x300000
	s_mul_i32 s98, s98, 0x2c0000
	s_add_u32 s99, s99, 0xd000000
	s_sub_u32 s99, s99, s98
	s_add_u32 s4, s4, s99
	s_addc_u32 s5, s5, 0

; #define LAS __attribute__((address_space(3)))
; __device__ __forceinline__ unsigned pk2(float lo, float hi) { const f32x2c v = {lo, hi}; const bf16x2c b = __builtin_convertvector(v, bf16x2c); return __builtin_bit_cast(unsigned, b); }
; #define lane (lane_now())
; __device__ __forceinline__ float wave_sum(float v) {
; #pragma unroll
;     for (int o = 1; o < 64; o <<= 1) v += __shfl_xor(v, o);
;     return v;
; }
; __device__ __forceinline__ void norm_phase(const float* src, const float* g, const float* mod, int ish, int isc, bf16_t* dst, LAS unsigned char* lds, int gw, int ngw, int wave, int lane) {
;     ...
;     for (int m = gw; m < MTOK; m += ngw) {
;         const f32x4* xr = (const f32x4*)(src + (size_t)m * DM) + lane;
;         f32x4 v[4]; float s = 0.f;
; #pragma unroll
;         for (int j = 0; j < 4; ++j) { v[j] = xr[64 * j]; s += (v[j].x * v[j].x + v[j].y * v[j].y) + (v[j].z * v[j].z + v[j].w * v[j].w); }
;         s = wave_sum(s);
;         const float rstd = rsqrtf(s * (1.f / DM) + 1e-6f);
;         const int bo = (m >> 13) * 1024;
;         u32x2* o8 = (u32x2*)(dst + (size_t)m * DM) + lane;
; #pragma unroll
;         for (int j = 0; j < 4; ++j) { const int c = bo + 4 * lane + 256 * j;
;             const f32x4 gg = *(const LAS f32x4*)(GSl + c), h4 = *(const LAS f32x4*)(SHl + c);
;             const f32x4 o = v[j] * rstd * gg + h4;
;             u32x2 w; w.x = pk2(o.x, o.y); w.y = pk2(o.z, o.w); o8[64 * j] = w; }
.Lxn_keep1247:
	v_and_b32_e32 v2, 64, v166
	v_add_u32_e32 v2, 64, v2
	v_xor_b32_e32 v3, 1, v166
	v_cmp_lt_i32_e32 vcc, v3, v2
	s_ashr_i32 s79, s78, 31
	s_lshl_b64 s[0:1], s[78:79], 11
	v_cndmask_b32_e32 v3, v166, v3, vcc
	v_lshlrev_b32_e32 v4, 2, v3
	v_xor_b32_e32 v3, 2, v166
	v_cmp_lt_i32_e32 vcc, v3, v2
	s_add_u32 s0, s92, s0
	v_ashrrev_i32_e32 v1, 31, v0
	v_cndmask_b32_e32 v3, v166, v3, vcc
	v_lshlrev_b32_e32 v5, 2, v3
	v_xor_b32_e32 v3, 4, v166
	v_cmp_lt_i32_e32 vcc, v3, v2
	s_addc_u32 s1, s93, s1
	s_ashr_i32 s85, s84, 31
	v_cndmask_b32_e32 v3, v166, v3, vcc
	v_lshlrev_b32_e32 v6, 2, v3
	v_xor_b32_e32 v3, 8, v166
	v_cmp_lt_i32_e32 vcc, v3, v2
	s_lshl_b64 s[6:7], s[78:79], 12
	v_lshlrev_b32_e32 v10, 2, v0
	v_cndmask_b32_e32 v3, v166, v3, vcc
	v_lshlrev_b32_e32 v7, 2, v3
	v_xor_b32_e32 v3, 16, v166
	v_cmp_lt_i32_e32 vcc, v3, v2
	v_mov_b32_e32 v11, 0x358637bd
	s_mov_b32 s8, 0x800000
	v_cndmask_b32_e32 v3, v166, v3, vcc
	v_lshlrev_b32_e32 v8, 2, v3
	v_xor_b32_e32 v3, 32, v166
	v_cmp_lt_i32_e32 vcc, v3, v2
	s_nop 1
	v_cndmask_b32_e32 v2, v166, v3, vcc
	v_lshlrev_b32_e32 v9, 2, v2
	v_lshl_add_u64 v[2:3], v[0:1], 3, s[0:1]
	s_mov_b64 s[0:1], 0xdb00000
	v_lshl_add_u64 v[2:3], v[2:3], 0, s[0:1]
	s_lshl_b64 s[0:1], s[84:85], 11
	s_add_u32 s6, s90, s6
	s_addc_u32 s7, s91, s7
	v_lshl_add_u64 v[0:1], v[0:1], 4, s[6:7]
	s_mov_b64 s[6:7], 0xc00
	v_lshl_add_u64 v[0:1], v[0:1], 0, s[6:7]
	s_lshl_b64 s[6:7], s[84:85], 12

; #define PG8_STAGE(bufoff, gbase, voff) do { _Pragma("unroll") for (int _i = 0; _i < 2; ++_i) \
;         __builtin_amdgcn_global_load_lds((const unsigned*)((const char*)(gbase) + (voff)[_i]), (PG8_LAS unsigned*)(lds + (bufoff) + ldsw + _i * 8192), 16, 0, 0); } while (0)
; #define PG8_WAIT_V(n) asm volatile("s_waitcnt vmcnt(" #n ")" ::: "memory")
; #define PG8_BAR __builtin_amdgcn_s_barrier()
; template <class Epi, class Sched, bool ALIGN_EPI = false, bool SP2 = false>
; __device__ __forceinline__ void gemm_phase(PG8_LAS unsigned char* lds, const Gemm g, const Sched& S, const Epi& E, const int wid) {
;     ...
;     for (int i = 0; i < 2; ++i) { int R, C; stage_rc(tid * 16 + i * 8192, R, C); const int Rb = Epi::PERM ? ((R & ~31) + perm32(R & 31)) : R;
;         voffA[i] = (unsigned)(R * K + C) * 2u; voffB[i] = (unsigned)(Rb * K + C) * 2u; }
;     const size_t kstep = (size_t)(BK * 2);
;     const size_t hstep = (size_t)HALF * K * 2;
;     const size_t tstep = 2 * hstep;
;     const unsigned ldsw = (unsigned)wid * 1024u;
;     const int aoff = lds_byte(wr * 64 + fr, fq * 8), boff = lds_byte(wc * 32 + fr, fq * 8);
;     ...
;     const char* cA = (const char*)g.A + (size_t)cur.pm * tstep; const char* cB = (const char*)g.Bt + (size_t)cur.pn * tstep;
;     S.a_ready(cur);
;     if constexpr (SP2) {
;         PG8_STAGE(PG8_SB(0, 0), cB, voffB); PG8_STAGE(PG8_SB(0, 1), cB + hstep, voffB); PG8_STAGE(PG8_SA(0, 0), cA, voffA); PG8_STAGE(PG8_SA(0, 1), cA + hstep, voffA);
;         if (wr == 1) PG8_BAR;
;         PG8_WAIT_V(2); PG8_BAR;
;         PG8_STAGE(PG8_SB(1, 0), cB + kstep, voffB); PG8_STAGE(PG8_SA(1, 0), cA + kstep, voffA); PG8_STAGE(PG8_SB(1, 1), cB + hstep + kstep, voffB);
.LBB0_1302:
	v_readlane_b32 s0, v244, 23
	v_readlane_b32 s1, v244, 24
	s_andn2_b64 vcc, exec, s[0:1]
	s_waitcnt lgkmcnt(0)
	s_barrier
	v_mbcnt_lo_u32_b32 v10, -1, 0
	v_mbcnt_hi_u32_b32 v10, -1, v10
	s_cbranch_vccnz .LBB0_1318
	v_lshl_add_u32 v0, v10, 4, s33
	v_add_u32_e32 v1, 0x2000, v0
	v_ashrrev_i32_e32 v2, 31, v1
	v_lshrrev_b32_e32 v2, 22, v2
	v_add_u32_e32 v2, v1, v2
	v_ashrrev_i32_e32 v8, 10, v2
	v_mul_i32_i24_e32 v2, 0x400, v8
	v_sub_u32_e32 v1, v1, v2
	v_lshrrev_b32_e32 v2, 4, v1
	v_bitop3_b32 v1, v2, v1, 32 bitop3:0x6c
	v_ashrrev_i32_e32 v2, 31, v1
	v_lshrrev_b32_e32 v2, 26, v2
	v_add_u32_e32 v2, v1, v2
	v_ashrrev_i32_e32 v9, 6, v2
	v_lshlrev_b32_e32 v3, 3, v8
	v_and_b32_e32 v2, 0xffc0, v2
	v_and_b32_e32 v3, -16, v3
	v_sub_u32_e32 v1, v1, v2
	v_add_u32_e32 v3, v9, v3
	v_lshrrev_b16_e32 v2, 7, v1
	v_and_b32_e32 v4, 3, v9
	s_mov_b32 s0, 0x1fffe0
	v_lshrrev_b32_e32 v5, 2, v3
	v_lshlrev_b32_e32 v6, 1, v3
	v_and_b32_e32 v2, 1, v2
	v_and_or_b32 v4, v3, s0, v4
	v_and_b32_e32 v5, 4, v5
	v_and_b32_e32 v6, 24, v6
	v_add_u16_e32 v1, v1, v2
	v_mov_b32_e32 v2, 1
	v_or3_b32 v4, v4, v5, v6
	v_lshlrev_b32_e32 v5, 5, v8
	v_ashrrev_i16_sdwa v1, v2, sext(v1) dst_sel:DWORD dst_unused:UNUSED_PAD src0_sel:DWORD src1_sel:BYTE_0
	v_and_b32_e32 v5, 32, v5
	v_bfe_i32 v11, v1, 0, 16
	v_add_lshl_u32 v1, v5, v11, 1
	v_lshl_add_u32 v128, v4, 11, v1
	v_lshl_add_u32 v130, v3, 11, v1
	v_ashrrev_i32_e32 v1, 31, v0
	v_lshrrev_b32_e32 v1, 22, v1
	v_add_u32_e32 v1, v0, v1
	v_ashrrev_i32_e32 v12, 10, v1
	v_mul_i32_i24_e32 v1, 0x400, v12
	v_sub_u32_e32 v0, v0, v1
	v_lshrrev_b32_e32 v1, 4, v0
	v_bitop3_b32 v0, v1, v0, 32 bitop3:0x6c
	v_ashrrev_i32_e32 v1, 31, v0
	v_lshrrev_b32_e32 v1, 26, v1
	v_add_u32_e32 v1, v0, v1
	v_lshlrev_b32_e32 v3, 3, v12
	s_add_u32 s28, s92, 0x1180000
	v_ashrrev_i32_e32 v13, 6, v1
	v_and_b32_e32 v3, -16, v3
	s_addc_u32 s29, s93, 0
	v_add_u32_e32 v3, v13, v3
	v_and_b32_e32 v4, 3, v13
	s_ashr_i32 s30, s68, 31
	v_and_or_b32 v4, v3, s0, v4
	s_lshr_b32 s0, s30, 29
	s_add_i32 s0, s68, s0
	s_ashr_i32 s1, s0, 3
	s_and_b32 s0, s0, -8
	s_sub_i32 s0, s68, s0
	s_cmp_lt_i32 s0, 0
	s_movk_i32 s31, 0x161
	s_cselect_b32 s6, s31, 0x160
	s_mul_i32 s0, s0, s6
	s_add_i32 s0, s0, s1
	s_mul_hi_i32 s1, s0, 0x2e8ba2e9
	s_lshr_b32 s6, s1, 31
	s_ashr_i32 s1, s1, 4
	s_add_i32 s1, s1, s6
	s_lshl_b32 s7, s1, 2
	s_mulk_i32 s1, 0x58
	s_sub_i32 s0, s0, s1
	s_bfe_i32 s1, s0, 0x80000
	s_bfe_u32 s1, s1, 0x2000d
	s_add_i32 s1, s0, s1
	s_bfe_i32 s6, s1, 0x80000
	s_and_b32 s1, s1, 0xfc
	s_sub_i32 s0, s0, s1
	s_sext_i32_i16 s6, s6
	s_sext_i32_i8 s0, s0
	v_lshrrev_b32_e32 v5, 2, v3
	v_lshlrev_b32_e32 v6, 1, v3
	v_and_b32_e32 v1, 0xc0, v1
	s_lshr_b32 s6, s6, 2
	s_add_i32 s20, s7, s0
	v_and_b32_e32 v5, 4, v5
	v_and_b32_e32 v6, 24, v6
	v_sub_u32_e32 v0, v0, v1
	s_ashr_i32 s21, s20, 31
	s_bfe_i64 s[8:9], s[6:7], 0x100000
	v_or3_b32 v4, v4, v5, v6
	v_lshlrev_b32_e32 v5, 5, v12
	v_ashrrev_i16_sdwa v0, v2, sext(v0) dst_sel:DWORD dst_unused:UNUSED_PAD src0_sel:DWORD src1_sel:BYTE_0
	s_lshl_b64 s[0:1], s[20:21], 19
	s_lshl_b64 s[8:9], s[8:9], 19
	v_and_b32_e32 v5, 32, v5
	v_bfe_i32 v14, v0, 0, 16
	s_add_u32 s24, s28, s8
	v_add_lshl_u32 v0, v5, v14, 1
	s_addc_u32 s25, s29, s9
	s_add_i32 s21, s33, 0
	v_lshl_add_u32 v132, v4, 11, v0
	s_add_i32 m0, s21, 0x10000
	v_lshl_add_u32 v134, v3, 11, v0
	global_load_lds_dwordx4 v132, s[24:25]
	s_add_i32 m0, s21, 0x12000
	s_add_u32 s8, s24, 0x40000
	global_load_lds_dwordx4 v128, s[24:25]
	s_addc_u32 s9, s25, 0
	s_add_i32 m0, s21, 0x14000
	v_mov_b32_e32 v133, 0
	global_load_lds_dwordx4 v132, s[8:9]
	s_add_i32 m0, s21, 0x16000
	s_add_u32 s22, s2, s0
	s_addc_u32 s23, s3, s1
	s_add_u32 s22, s22, 0xb000000
	s_addc_u32 s23, s23, 0
	s_add_i32 s34, s21, 0x2000
	global_load_lds_dwordx4 v128, s[8:9]
	s_mov_b32 m0, s21
	s_add_u32 s0, s22, 0x40000
	global_load_lds_dwordx4 v134, s[22:23]
	s_mov_b32 m0, s34
	s_addc_u32 s1, s23, 0
	s_add_i32 s35, s21, 0x4000
	global_load_lds_dwordx4 v130, s[22:23]
	s_mov_b32 m0, s35
	s_add_i32 s36, s21, 0x6000
	global_load_lds_dwordx4 v134, s[0:1]
	s_mov_b32 m0, s36
	v_readlane_b32 s7, v244, 18
	global_load_lds_dwordx4 v130, s[0:1]
	v_mov_b32_e32 v129, v133
	v_mov_b32_e32 v135, v133
	v_mov_b32_e32 v131, v133
	s_cmp_eq_u32 s7, 1
	s_mov_b32 s37, 0
	v_lshl_add_u64 v[4:5], s[24:25], 0, v[132:133]
	v_lshl_add_u64 v[2:3], s[24:25], 0, v[128:129]
	v_lshl_add_u64 v[0:1], s[22:23], 0, v[134:135]
	s_cselect_b64 s[0:1], -1, 0
	s_cmp_lg_u32 s7, 1
	v_lshl_add_u64 v[6:7], s[22:23], 0, v[130:131]
	s_cbranch_scc1 .LBB0_1305
	s_barrier

; template <class Epi, class Sched, bool ALIGN_EPI = false, bool SP2 = false>
; __device__ __forceinline__ void gemm_phase(PG8_LAS unsigned char* lds, const Gemm g, const Sched& S, const Epi& E, const int wid) {
;     ...
;         const bool has_next = S.next(ui + 1, nxt);
;         const char* nA = has_next ? (const char*)g.A + (size_t)nxt.pm * tstep : cA; const char* nB = has_next ? (const char*)g.Bt + (size_t)nxt.pn * tstep : cB;
;         for (int t = 0; t < nt; t += 2) {
;             const bool last = (t == nt - 2);
;             const char* a1 = cA + (size_t)(t + 1) * kstep;
;             const char* a2 = last ? nA : cA + (size_t)(t + 2) * kstep; const char* b2 = last ? nB : cB + (size_t)(t + 2) * kstep;
;             const char* a3 = a2 + kstep; const char* b3 = b2 + kstep;
;             if (last && has_next) S.a_ready(nxt);
;     ...
; #pragma unroll
;         for (int a = 0; a < 2; ++a)
; #pragma unroll
;             for (int b = 0; b < 2; ++b)
; #pragma unroll
;                 for (int m = 0; m < 4; ++m)
; #pragma unroll
;                     for (int n = 0; n < 2; ++n) acc[a][b][m][n] = (f32x4){0.f, 0.f, 0.f, 0.f};
;         cur = nxt; cA = nA; cB = nB; ++ui;
.LBB0_1310:
	s_ashr_i32 s15, s14, 31
	s_lshl_b64 s[16:17], s[14:15], 19
	s_add_u32 s16, s2, s16
	s_addc_u32 s17, s3, s17
	s_add_u32 s16, s16, 0xb000000
	s_addc_u32 s17, s17, 0
	s_and_b64 s[18:19], s[6:7], exec
	s_cselect_b32 s15, s17, s23
	s_cselect_b32 s46, s16, s22
	s_ashr_i32 s13, s12, 31
	s_lshl_b64 s[18:19], s[12:13], 19
	s_add_u32 s18, s28, s18
	s_addc_u32 s19, s29, s19
	s_and_b64 s[26:27], s[6:7], exec
	s_cselect_b32 s13, s19, s25
	s_cselect_b32 s47, s18, s24
	s_add_u32 s22, s22, 0x40080
	s_addc_u32 s23, s23, 0
	s_add_u32 s48, s24, 0x100
	v_mov_b32_e32 v0, 0
	s_addc_u32 s49, s25, 0
	s_mov_b32 s50, -2
	v_mov_b32_e32 v1, v0
	v_mov_b32_e32 v2, v0
	v_mov_b32_e32 v3, v0
	v_mov_b32_e32 v8, v0
	v_mov_b32_e32 v9, v0
	v_mov_b32_e32 v10, v0
	v_mov_b32_e32 v11, v0
	v_mov_b32_e32 v16, v0
	v_mov_b32_e32 v17, v0
	v_mov_b32_e32 v18, v0
	v_mov_b32_e32 v19, v0
	v_mov_b32_e32 v24, v0
	v_mov_b32_e32 v25, v0
	v_mov_b32_e32 v26, v0
	v_mov_b32_e32 v27, v0
	v_mov_b32_e32 v32, v0
	v_mov_b32_e32 v33, v0
	v_mov_b32_e32 v34, v0
	v_mov_b32_e32 v35, v0
	v_mov_b32_e32 v40, v0
	v_mov_b32_e32 v41, v0
	v_mov_b32_e32 v42, v0
	v_mov_b32_e32 v43, v0
	v_mov_b32_e32 v48, v0
	v_mov_b32_e32 v49, v0
	v_mov_b32_e32 v50, v0
	v_mov_b32_e32 v51, v0
	v_mov_b32_e32 v56, v0
	v_mov_b32_e32 v57, v0
	v_mov_b32_e32 v58, v0
	v_mov_b32_e32 v59, v0
	v_mov_b32_e32 v4, v0
	v_mov_b32_e32 v5, v0
	v_mov_b32_e32 v6, v0
	v_mov_b32_e32 v7, v0
	v_mov_b32_e32 v12, v0
	v_mov_b32_e32 v13, v0
	v_mov_b32_e32 v14, v0
	v_mov_b32_e32 v15, v0
	v_mov_b32_e32 v20, v0
	v_mov_b32_e32 v21, v0
	v_mov_b32_e32 v22, v0
	v_mov_b32_e32 v23, v0
	v_mov_b32_e32 v28, v0
	v_mov_b32_e32 v29, v0
	v_mov_b32_e32 v30, v0
	v_mov_b32_e32 v31, v0
	v_mov_b32_e32 v36, v0
	v_mov_b32_e32 v37, v0
	v_mov_b32_e32 v38, v0
	v_mov_b32_e32 v39, v0
	v_mov_b32_e32 v44, v0
	v_mov_b32_e32 v45, v0
	v_mov_b32_e32 v46, v0
	v_mov_b32_e32 v47, v0
	v_mov_b32_e32 v52, v0
	v_mov_b32_e32 v53, v0
	v_mov_b32_e32 v54, v0
	v_mov_b32_e32 v55, v0
	v_mov_b32_e32 v60, v0
	v_mov_b32_e32 v61, v0
	v_mov_b32_e32 v62, v0
	v_mov_b32_e32 v63, v0
	v_mov_b32_e32 v64, v0
	v_mov_b32_e32 v65, v0
	v_mov_b32_e32 v66, v0
	v_mov_b32_e32 v67, v0
	v_mov_b32_e32 v72, v0
	v_mov_b32_e32 v73, v0
	v_mov_b32_e32 v74, v0
	v_mov_b32_e32 v75, v0
	v_mov_b32_e32 v80, v0
	v_mov_b32_e32 v81, v0
	v_mov_b32_e32 v82, v0
	v_mov_b32_e32 v83, v0
	v_mov_b32_e32 v88, v0
	v_mov_b32_e32 v89, v0
	v_mov_b32_e32 v90, v0
	v_mov_b32_e32 v91, v0
	v_mov_b32_e32 v96, v0
	v_mov_b32_e32 v97, v0
	v_mov_b32_e32 v98, v0
	v_mov_b32_e32 v99, v0
	v_mov_b32_e32 v104, v0
	v_mov_b32_e32 v105, v0
	v_mov_b32_e32 v106, v0
	v_mov_b32_e32 v107, v0
	v_mov_b32_e32 v112, v0
	v_mov_b32_e32 v113, v0
	v_mov_b32_e32 v114, v0
	v_mov_b32_e32 v115, v0
	v_mov_b32_e32 v120, v0
	v_mov_b32_e32 v121, v0
	v_mov_b32_e32 v122, v0
	v_mov_b32_e32 v123, v0
	v_mov_b32_e32 v68, v0
	v_mov_b32_e32 v69, v0
	v_mov_b32_e32 v70, v0
	v_mov_b32_e32 v71, v0
	v_mov_b32_e32 v76, v0
	v_mov_b32_e32 v77, v0
	v_mov_b32_e32 v78, v0
	v_mov_b32_e32 v79, v0
	v_mov_b32_e32 v84, v0
	v_mov_b32_e32 v85, v0
	v_mov_b32_e32 v86, v0
	v_mov_b32_e32 v87, v0
	v_mov_b32_e32 v92, v0
	v_mov_b32_e32 v93, v0
	v_mov_b32_e32 v94, v0
	v_mov_b32_e32 v95, v0
	v_mov_b32_e32 v100, v0
	v_mov_b32_e32 v101, v0
	v_mov_b32_e32 v102, v0
	v_mov_b32_e32 v103, v0
	v_mov_b32_e32 v108, v0
	v_mov_b32_e32 v109, v0
	v_mov_b32_e32 v110, v0
	v_mov_b32_e32 v111, v0
	v_mov_b32_e32 v116, v0
	v_mov_b32_e32 v117, v0
	v_mov_b32_e32 v118, v0
	v_mov_b32_e32 v119, v0
	v_mov_b32_e32 v124, v0
	v_mov_b32_e32 v125, v0
	v_mov_b32_e32 v126, v0
	v_mov_b32_e32 v127, v0

; __device__ __forceinline__ unsigned pk2(float lo, float hi) { const f32x2c v = {lo, hi}; const bf16x2c b = __builtin_convertvector(v, bf16x2c); return __builtin_bit_cast(unsigned, b); }
; __device__ __forceinline__ float silu_f(float x) { return x * fast_sigmoid(x); }
;     __device__ __forceinline__ void operator()(const f32x4 (&acc)[2][2][4][2], const pg8::Unit& u, int wr, int wc, int fr, int fq) const {
;         const int row0 = u.pm * 256 + wr * 64 + fr, col0 = u.pn * 128 + wc * 32 + 8 * fq;
; #pragma unroll
;         for (int ai = 0; ai < 2; ++ai)
; #pragma unroll
;             for (int m = 0; m < 4; ++m) {
;                 bf16_t* rowp = O + (size_t)(row0 + ai * 128 + m * 16) * ldc + col0;
;                 const f32x4 a0 = acc[ai][0][m][0], a1 = acc[ai][0][m][1], b0 = acc[ai][1][m][0], b1 = acc[ai][1][m][1];
;                 u32x4 w;
;                 w.x = pk2(silu_f(a0[0]) * b0[0], silu_f(a0[1]) * b0[1]); w.y = pk2(silu_f(a0[2]) * b0[2], silu_f(a0[3]) * b0[3]);
;                 w.z = pk2(silu_f(a1[0]) * b1[0], silu_f(a1[1]) * b1[1]); w.w = pk2(silu_f(a1[2]) * b1[2], silu_f(a1[3]) * b1[3]);
;                 *(u32x4*)rowp = w;
;             }
.LBB0_1314:
	v_mul_f32_e32 v155, 0xbfb8aa3b, v124
	v_exp_f32_e32 v155, v155
	v_mul_f32_e32 v158, 0xbfb8aa3b, v125
	v_exp_f32_e32 v159, v158
	v_lshl_add_u32 v154, s20, 8, v148
	v_add_f32_e32 v155, 1.0, v155
	v_rcp_f32_e32 v158, v155
	v_add_f32_e32 v155, 1.0, v159
	v_mul_f32_e32 v159, 0xbfb8aa3b, v126
	v_exp_f32_e32 v160, v159
	v_mul_f32_e32 v159, 0xbfb8aa3b, v127
	v_exp_f32_e32 v161, v159
	v_rcp_f32_e32 v159, v155
	v_add_f32_e32 v155, 1.0, v160
	v_rcp_f32_e32 v160, v155
	v_add_f32_e32 v155, 1.0, v161
	v_rcp_f32_e32 v161, v155
	v_pk_mul_f32 v[124:125], v[124:125], v[158:159]
	v_lshl_add_u32 v144, s45, 7, v150
	v_pk_mul_f32 v[120:121], v[124:125], v[120:121]
	v_pk_mul_f32 v[124:125], v[126:127], v[160:161]
	v_cvt_pk_bf16_f32 v120, v120, v121
	v_mul_f32_e32 v121, 0xbfb8aa3b, v116
	v_pk_mul_f32 v[122:123], v[124:125], v[122:123]
	v_exp_f32_e32 v124, v121
	v_mul_f32_e32 v121, 0xbfb8aa3b, v117
	v_exp_f32_e32 v125, v121
	v_cvt_pk_bf16_f32 v121, v122, v123
	v_add_f32_e32 v122, 1.0, v124
	v_mul_f32_e32 v124, 0xbfb8aa3b, v118
	v_add_f32_e32 v123, 1.0, v125
	v_mul_f32_e32 v125, 0xbfb8aa3b, v119
	v_exp_f32_e32 v124, v124
	v_exp_f32_e32 v125, v125
	v_rcp_f32_e32 v122, v122
	v_rcp_f32_e32 v123, v123
	v_add_f32_e32 v124, 1.0, v124
	v_add_f32_e32 v125, 1.0, v125
	v_rcp_f32_e32 v124, v124
	v_rcp_f32_e32 v125, v125
	v_pk_mul_f32 v[116:117], v[116:117], v[122:123]
	v_ashrrev_i32_e32 v145, 31, v144
	v_pk_mul_f32 v[112:113], v[116:117], v[112:113]
	v_mul_f32_e32 v116, 0xbfb8aa3b, v110
	v_cvt_pk_bf16_f32 v122, v112, v113
	v_pk_mul_f32 v[112:113], v[118:119], v[124:125]
	v_mul_f32_e32 v117, 0xbfb8aa3b, v111
	v_pk_mul_f32 v[112:113], v[112:113], v[114:115]
	v_mul_f32_e32 v114, 0xbfb8aa3b, v108
	v_mul_f32_e32 v115, 0xbfb8aa3b, v109
	v_exp_f32_e32 v114, v114
	v_exp_f32_e32 v115, v115
	v_exp_f32_e32 v116, v116
	v_exp_f32_e32 v117, v117
	v_add_f32_e32 v114, 1.0, v114
	v_add_f32_e32 v115, 1.0, v115
	v_rcp_f32_e32 v114, v114
	v_rcp_f32_e32 v115, v115
	v_add_f32_e32 v116, 1.0, v116
	v_add_f32_e32 v117, 1.0, v117
	v_rcp_f32_e32 v116, v116
	v_rcp_f32_e32 v117, v117
	v_pk_mul_f32 v[108:109], v[108:109], v[114:115]
	s_cselect_b32 s98, 1, 0
	s_lshr_b32 s99, s20, 1
	s_and_b32 s100, s99, 7
	s_lshl_b32 s100, s100, 1
	s_bfe_u32 s101, s99, 0x10003
	s_or_b32 s100, s100, s101
	s_and_b32 s101, s99, 0x30
	s_or_b32 s100, s100, s101
	s_mul_i32 s100, s100, 0x300000
	s_mul_i32 s99, s99, 0x2c0000
	s_add_u32 s100, s100, 0xd000000
	s_sub_u32 s100, s100, s99
	s_add_u32 s100, s96, s100
	s_addc_u32 s101, s97, 0
	s_cmp_lg_u32 s98, 0
	v_mov_b64_e32 v[146:147], s[100:101]
	v_pk_mul_f32 v[104:105], v[108:109], v[104:105]
	v_pk_mul_f32 v[108:109], v[110:111], v[116:117]
	v_cvt_pk_bf16_f32 v104, v104, v105
	v_mul_f32_e32 v105, 0xbfb8aa3b, v100
	v_pk_mul_f32 v[106:107], v[108:109], v[106:107]
	v_exp_f32_e32 v108, v105
	v_mul_f32_e32 v105, 0xbfb8aa3b, v101
	v_exp_f32_e32 v109, v105
	v_cvt_pk_bf16_f32 v105, v106, v107
	v_add_f32_e32 v106, 1.0, v108
	v_mul_f32_e32 v108, 0xbfb8aa3b, v102
	v_add_f32_e32 v107, 1.0, v109
	v_mul_f32_e32 v109, 0xbfb8aa3b, v103
	v_exp_f32_e32 v108, v108
	v_exp_f32_e32 v109, v109
	v_rcp_f32_e32 v106, v106
	v_rcp_f32_e32 v107, v107
	v_add_f32_e32 v108, 1.0, v108
	v_add_f32_e32 v109, 1.0, v109
	v_rcp_f32_e32 v108, v108
	v_rcp_f32_e32 v109, v109
	v_pk_mul_f32 v[100:101], v[100:101], v[106:107]
	v_cvt_pk_bf16_f32 v123, v112, v113
	v_pk_mul_f32 v[96:97], v[100:101], v[96:97]
	v_mul_f32_e32 v100, 0xbfb8aa3b, v94
	v_cvt_pk_bf16_f32 v106, v96, v97
	v_pk_mul_f32 v[96:97], v[102:103], v[108:109]
	v_mul_f32_e32 v101, 0xbfb8aa3b, v95
	v_pk_mul_f32 v[96:97], v[96:97], v[98:99]
	v_mul_f32_e32 v98, 0xbfb8aa3b, v92
	v_mul_f32_e32 v99, 0xbfb8aa3b, v93
	v_exp_f32_e32 v98, v98
	v_exp_f32_e32 v99, v99
	v_exp_f32_e32 v100, v100
	v_exp_f32_e32 v101, v101
	v_add_f32_e32 v98, 1.0, v98
	v_add_f32_e32 v99, 1.0, v99
	v_rcp_f32_e32 v98, v98
	v_rcp_f32_e32 v99, v99
	v_add_f32_e32 v100, 1.0, v100
	v_add_f32_e32 v101, 1.0, v101
	v_rcp_f32_e32 v100, v100
	v_rcp_f32_e32 v101, v101
	v_pk_mul_f32 v[92:93], v[92:93], v[98:99]
	v_or_b32_e32 v112, 16, v154
	v_pk_mul_f32 v[88:89], v[92:93], v[88:89]
	v_pk_mul_f32 v[92:93], v[94:95], v[100:101]
	v_cvt_pk_bf16_f32 v88, v88, v89
	v_mul_f32_e32 v89, 0xbfb8aa3b, v84
	v_pk_mul_f32 v[90:91], v[92:93], v[90:91]
	v_exp_f32_e32 v92, v89
	v_mul_f32_e32 v89, 0xbfb8aa3b, v85
	v_exp_f32_e32 v93, v89
	v_cvt_pk_bf16_f32 v89, v90, v91
	v_add_f32_e32 v90, 1.0, v92
	v_mul_f32_e32 v92, 0xbfb8aa3b, v86
	v_add_f32_e32 v91, 1.0, v93
	v_mul_f32_e32 v93, 0xbfb8aa3b, v87
	v_exp_f32_e32 v92, v92
	v_exp_f32_e32 v93, v93
	v_rcp_f32_e32 v90, v90
	v_rcp_f32_e32 v91, v91
	v_add_f32_e32 v92, 1.0, v92
	v_add_f32_e32 v93, 1.0, v93
	v_rcp_f32_e32 v92, v92
	v_rcp_f32_e32 v93, v93
	v_pk_mul_f32 v[84:85], v[84:85], v[90:91]
	v_cvt_pk_bf16_f32 v107, v96, v97
	v_pk_mul_f32 v[80:81], v[84:85], v[80:81]
	v_mul_f32_e32 v84, 0xbfb8aa3b, v78
	v_cvt_pk_bf16_f32 v90, v80, v81
	v_pk_mul_f32 v[80:81], v[86:87], v[92:93]
	v_mul_f32_e32 v85, 0xbfb8aa3b, v79
	v_pk_mul_f32 v[80:81], v[80:81], v[82:83]
	v_mul_f32_e32 v82, 0xbfb8aa3b, v76
	v_mul_f32_e32 v83, 0xbfb8aa3b, v77
	v_exp_f32_e32 v82, v82
	v_exp_f32_e32 v83, v83
	v_exp_f32_e32 v84, v84
	v_exp_f32_e32 v85, v85
	v_add_f32_e32 v82, 1.0, v82
	v_add_f32_e32 v83, 1.0, v83
	v_rcp_f32_e32 v82, v82
	v_rcp_f32_e32 v83, v83
	v_add_f32_e32 v84, 1.0, v84
	v_add_f32_e32 v85, 1.0, v85
	v_rcp_f32_e32 v84, v84
	v_rcp_f32_e32 v85, v85
	v_pk_mul_f32 v[76:77], v[76:77], v[82:83]
	v_or_b32_e32 v96, 32, v154
	v_pk_mul_f32 v[72:73], v[76:77], v[72:73]
	v_pk_mul_f32 v[76:77], v[78:79], v[84:85]
	v_cvt_pk_bf16_f32 v72, v72, v73
	v_mul_f32_e32 v73, 0xbfb8aa3b, v68
; __device__ __forceinline__ unsigned pk2(float lo, float hi) { const f32x2c v = {lo, hi}; const bf16x2c b = __builtin_convertvector(v, bf16x2c); return __builtin_bit_cast(unsigned, b); }
; __device__ __forceinline__ float silu_f(float x) { return x * fast_sigmoid(x); }
;     __device__ __forceinline__ void operator()(const f32x4 (&acc)[2][2][4][2], const pg8::Unit& u, int wr, int wc, int fr, int fq) const {
;         const int row0 = u.pm * 256 + wr * 64 + fr, col0 = u.pn * 128 + wc * 32 + 8 * fq;
; #pragma unroll
;         for (int ai = 0; ai < 2; ++ai)
; #pragma unroll
;             for (int m = 0; m < 4; ++m) {
;                 bf16_t* rowp = O + (size_t)(row0 + ai * 128 + m * 16) * ldc + col0;
;                 const f32x4 a0 = acc[ai][0][m][0], a1 = acc[ai][0][m][1], b0 = acc[ai][1][m][0], b1 = acc[ai][1][m][1];
;                 u32x4 w;
;                 w.x = pk2(silu_f(a0[0]) * b0[0], silu_f(a0[1]) * b0[1]); w.y = pk2(silu_f(a0[2]) * b0[2], silu_f(a0[3]) * b0[3]);
;                 w.z = pk2(silu_f(a1[0]) * b1[0], silu_f(a1[1]) * b1[1]); w.w = pk2(silu_f(a1[2]) * b1[2], silu_f(a1[3]) * b1[3]);
;                 *(u32x4*)rowp = w;
;             }
	v_pk_mul_f32 v[74:75], v[76:77], v[74:75]
	v_exp_f32_e32 v76, v73
	v_mul_f32_e32 v73, 0xbfb8aa3b, v69
	v_exp_f32_e32 v77, v73
	v_cvt_pk_bf16_f32 v73, v74, v75
	v_add_f32_e32 v74, 1.0, v76
	v_mul_f32_e32 v76, 0xbfb8aa3b, v70
	v_add_f32_e32 v75, 1.0, v77
	v_mul_f32_e32 v77, 0xbfb8aa3b, v71
	v_exp_f32_e32 v76, v76
	v_exp_f32_e32 v77, v77
	v_rcp_f32_e32 v74, v74
	v_rcp_f32_e32 v75, v75
	v_add_f32_e32 v76, 1.0, v76
	v_add_f32_e32 v77, 1.0, v77
	v_rcp_f32_e32 v76, v76
	v_rcp_f32_e32 v77, v77
	v_pk_mul_f32 v[68:69], v[68:69], v[74:75]
	v_cvt_pk_bf16_f32 v91, v80, v81
	v_pk_mul_f32 v[64:65], v[68:69], v[64:65]
	v_mul_f32_e32 v68, 0xbfb8aa3b, v62
	v_cvt_pk_bf16_f32 v74, v64, v65
	v_pk_mul_f32 v[64:65], v[70:71], v[76:77]
	v_mul_f32_e32 v69, 0xbfb8aa3b, v63
	v_pk_mul_f32 v[64:65], v[64:65], v[66:67]
	v_mul_f32_e32 v66, 0xbfb8aa3b, v60
	v_mul_f32_e32 v67, 0xbfb8aa3b, v61
	v_exp_f32_e32 v66, v66
	v_exp_f32_e32 v67, v67
	v_exp_f32_e32 v68, v68
	v_exp_f32_e32 v69, v69
	v_add_f32_e32 v66, 1.0, v66
	v_add_f32_e32 v67, 1.0, v67
	v_rcp_f32_e32 v66, v66
	v_rcp_f32_e32 v67, v67
	v_add_f32_e32 v68, 1.0, v68
	v_add_f32_e32 v69, 1.0, v69
	v_rcp_f32_e32 v68, v68
	v_rcp_f32_e32 v69, v69
	v_pk_mul_f32 v[60:61], v[60:61], v[66:67]
	v_or_b32_e32 v80, 48, v154
	v_pk_mul_f32 v[56:57], v[60:61], v[56:57]
	v_pk_mul_f32 v[60:61], v[62:63], v[68:69]
	v_cvt_pk_bf16_f32 v56, v56, v57
	v_mul_f32_e32 v57, 0xbfb8aa3b, v52
	v_pk_mul_f32 v[58:59], v[60:61], v[58:59]
	v_exp_f32_e32 v60, v57
	v_mul_f32_e32 v57, 0xbfb8aa3b, v53
	v_exp_f32_e32 v61, v57
	v_cvt_pk_bf16_f32 v57, v58, v59
	v_add_f32_e32 v58, 1.0, v60
	v_mul_f32_e32 v60, 0xbfb8aa3b, v54
	v_add_f32_e32 v59, 1.0, v61
	v_mul_f32_e32 v61, 0xbfb8aa3b, v55
	v_exp_f32_e32 v60, v60
	v_exp_f32_e32 v61, v61
	v_rcp_f32_e32 v58, v58
	v_rcp_f32_e32 v59, v59
	v_add_f32_e32 v60, 1.0, v60
	v_add_f32_e32 v61, 1.0, v61
	v_rcp_f32_e32 v60, v60
	v_rcp_f32_e32 v61, v61
	v_pk_mul_f32 v[52:53], v[52:53], v[58:59]
	v_cvt_pk_bf16_f32 v75, v64, v65
	v_pk_mul_f32 v[48:49], v[52:53], v[48:49]
	v_mul_f32_e32 v52, 0xbfb8aa3b, v46
	v_cvt_pk_bf16_f32 v58, v48, v49
	v_pk_mul_f32 v[48:49], v[54:55], v[60:61]
	v_mul_f32_e32 v53, 0xbfb8aa3b, v47
	v_pk_mul_f32 v[48:49], v[48:49], v[50:51]
	v_mul_f32_e32 v50, 0xbfb8aa3b, v44
	v_mul_f32_e32 v51, 0xbfb8aa3b, v45
	v_exp_f32_e32 v50, v50
	v_exp_f32_e32 v51, v51
	v_exp_f32_e32 v52, v52
	v_exp_f32_e32 v53, v53
	v_add_f32_e32 v50, 1.0, v50
	v_add_f32_e32 v51, 1.0, v51
	v_rcp_f32_e32 v50, v50
	v_rcp_f32_e32 v51, v51
	v_add_f32_e32 v52, 1.0, v52
	v_add_f32_e32 v53, 1.0, v53
	v_rcp_f32_e32 v52, v52
	v_rcp_f32_e32 v53, v53
	v_pk_mul_f32 v[44:45], v[44:45], v[50:51]
	v_add_u32_e32 v64, 0x80, v154
	v_pk_mul_f32 v[40:41], v[44:45], v[40:41]
	v_pk_mul_f32 v[44:45], v[46:47], v[52:53]
	v_cvt_pk_bf16_f32 v40, v40, v41
	v_mul_f32_e32 v41, 0xbfb8aa3b, v36
	v_pk_mul_f32 v[42:43], v[44:45], v[42:43]
	v_exp_f32_e32 v44, v41
	v_mul_f32_e32 v41, 0xbfb8aa3b, v37
	v_exp_f32_e32 v45, v41
	v_cvt_pk_bf16_f32 v41, v42, v43
	v_add_f32_e32 v42, 1.0, v44
	v_mul_f32_e32 v44, 0xbfb8aa3b, v38
	v_add_f32_e32 v43, 1.0, v45
	v_mul_f32_e32 v45, 0xbfb8aa3b, v39
	v_exp_f32_e32 v44, v44
	v_exp_f32_e32 v45, v45
	v_rcp_f32_e32 v42, v42
	v_rcp_f32_e32 v43, v43
	v_add_f32_e32 v44, 1.0, v44
	v_add_f32_e32 v45, 1.0, v45
	v_rcp_f32_e32 v44, v44
	v_rcp_f32_e32 v45, v45
	v_pk_mul_f32 v[36:37], v[36:37], v[42:43]
	v_cvt_pk_bf16_f32 v59, v48, v49
	v_pk_mul_f32 v[32:33], v[36:37], v[32:33]
	v_mul_f32_e32 v36, 0xbfb8aa3b, v30
	v_cvt_pk_bf16_f32 v42, v32, v33
	v_pk_mul_f32 v[32:33], v[38:39], v[44:45]
	v_mul_f32_e32 v37, 0xbfb8aa3b, v31
	v_pk_mul_f32 v[32:33], v[32:33], v[34:35]
	v_mul_f32_e32 v34, 0xbfb8aa3b, v28
	v_mul_f32_e32 v35, 0xbfb8aa3b, v29
	v_exp_f32_e32 v34, v34
	v_exp_f32_e32 v35, v35
	v_exp_f32_e32 v36, v36
	v_exp_f32_e32 v37, v37
	v_add_f32_e32 v34, 1.0, v34
	v_add_f32_e32 v35, 1.0, v35
	v_rcp_f32_e32 v34, v34
	v_rcp_f32_e32 v35, v35
	v_add_f32_e32 v36, 1.0, v36
; __device__ __forceinline__ unsigned pk2(float lo, float hi) { const f32x2c v = {lo, hi}; const bf16x2c b = __builtin_convertvector(v, bf16x2c); return __builtin_bit_cast(unsigned, b); }
; __device__ __forceinline__ float silu_f(float x) { return x * fast_sigmoid(x); }
; template <class Epi, class Sched, bool ALIGN_EPI = false, bool SP2 = false>
; __device__ __forceinline__ void gemm_phase(PG8_LAS unsigned char* lds, const Gemm g, const Sched& S, const Epi& E, const int wid) {
;     ...
;         if constexpr (!Epi::AFTER_DRAIN) { E(acc, cur, wr, wc, fr, fq); S.done(cur); }
;         if (!has_next) break;
;     __device__ __forceinline__ void operator()(const f32x4 (&acc)[2][2][4][2], const pg8::Unit& u, int wr, int wc, int fr, int fq) const {
;         const int row0 = u.pm * 256 + wr * 64 + fr, col0 = u.pn * 128 + wc * 32 + 8 * fq;
; #pragma unroll
;         for (int ai = 0; ai < 2; ++ai)
; #pragma unroll
;             for (int m = 0; m < 4; ++m) {
;                 bf16_t* rowp = O + (size_t)(row0 + ai * 128 + m * 16) * ldc + col0;
;                 const f32x4 a0 = acc[ai][0][m][0], a1 = acc[ai][0][m][1], b0 = acc[ai][1][m][0], b1 = acc[ai][1][m][1];
;                 u32x4 w;
;                 w.x = pk2(silu_f(a0[0]) * b0[0], silu_f(a0[1]) * b0[1]); w.y = pk2(silu_f(a0[2]) * b0[2], silu_f(a0[3]) * b0[3]);
;                 w.z = pk2(silu_f(a1[0]) * b1[0], silu_f(a1[1]) * b1[1]); w.w = pk2(silu_f(a1[2]) * b1[2], silu_f(a1[3]) * b1[3]);
;                 *(u32x4*)rowp = w;
;             }
	v_add_f32_e32 v37, 1.0, v37
	v_rcp_f32_e32 v36, v36
	v_rcp_f32_e32 v37, v37
	v_pk_mul_f32 v[28:29], v[28:29], v[34:35]
	v_add_u32_e32 v48, 0x90, v154
	v_pk_mul_f32 v[24:25], v[28:29], v[24:25]
	v_pk_mul_f32 v[28:29], v[30:31], v[36:37]
	v_cvt_pk_bf16_f32 v24, v24, v25
	v_mul_f32_e32 v25, 0xbfb8aa3b, v20
	v_pk_mul_f32 v[26:27], v[28:29], v[26:27]
	v_exp_f32_e32 v28, v25
	v_mul_f32_e32 v25, 0xbfb8aa3b, v21
	v_exp_f32_e32 v29, v25
	v_cvt_pk_bf16_f32 v25, v26, v27
	v_add_f32_e32 v26, 1.0, v28
	v_mul_f32_e32 v28, 0xbfb8aa3b, v22
	v_add_f32_e32 v27, 1.0, v29
	v_mul_f32_e32 v29, 0xbfb8aa3b, v23
	v_exp_f32_e32 v28, v28
	v_exp_f32_e32 v29, v29
	v_rcp_f32_e32 v26, v26
	v_rcp_f32_e32 v27, v27
	v_add_f32_e32 v28, 1.0, v28
	v_add_f32_e32 v29, 1.0, v29
	v_rcp_f32_e32 v28, v28
	v_rcp_f32_e32 v29, v29
	v_pk_mul_f32 v[20:21], v[20:21], v[26:27]
	v_cvt_pk_bf16_f32 v43, v32, v33
	v_pk_mul_f32 v[16:17], v[20:21], v[16:17]
	v_mul_f32_e32 v20, 0xbfb8aa3b, v14
	v_cvt_pk_bf16_f32 v26, v16, v17
	v_pk_mul_f32 v[16:17], v[22:23], v[28:29]
	v_mul_f32_e32 v21, 0xbfb8aa3b, v15
	v_pk_mul_f32 v[16:17], v[16:17], v[18:19]
	v_mul_f32_e32 v18, 0xbfb8aa3b, v12
	v_mul_f32_e32 v19, 0xbfb8aa3b, v13
	v_exp_f32_e32 v18, v18
	v_exp_f32_e32 v19, v19
	v_exp_f32_e32 v20, v20
	v_exp_f32_e32 v21, v21
	v_add_f32_e32 v18, 1.0, v18
	v_add_f32_e32 v19, 1.0, v19
	v_rcp_f32_e32 v18, v18
	v_rcp_f32_e32 v19, v19
	v_add_f32_e32 v20, 1.0, v20
	v_add_f32_e32 v21, 1.0, v21
	v_rcp_f32_e32 v20, v20
	v_rcp_f32_e32 v21, v21
	v_pk_mul_f32 v[12:13], v[12:13], v[18:19]
	v_add_u32_e32 v32, 0xa0, v154
	v_pk_mul_f32 v[8:9], v[12:13], v[8:9]
	v_pk_mul_f32 v[12:13], v[14:15], v[20:21]
	v_cvt_pk_bf16_f32 v8, v8, v9
	v_mul_f32_e32 v9, 0xbfb8aa3b, v4
	v_pk_mul_f32 v[10:11], v[12:13], v[10:11]
	v_exp_f32_e32 v12, v9
	v_mul_f32_e32 v9, 0xbfb8aa3b, v5
	v_exp_f32_e32 v13, v9
	v_cvt_pk_bf16_f32 v9, v10, v11
	v_add_f32_e32 v10, 1.0, v12
	v_mul_f32_e32 v12, 0xbfb8aa3b, v6
	v_add_f32_e32 v11, 1.0, v13
	v_mul_f32_e32 v13, 0xbfb8aa3b, v7
	v_exp_f32_e32 v12, v12
	v_exp_f32_e32 v13, v13
	v_rcp_f32_e32 v10, v10
	v_rcp_f32_e32 v11, v11
	v_add_f32_e32 v12, 1.0, v12
	v_add_f32_e32 v13, 1.0, v13
	v_rcp_f32_e32 v12, v12
	v_rcp_f32_e32 v13, v13
	v_pk_mul_f32 v[4:5], v[4:5], v[10:11]
	v_cvt_pk_bf16_f32 v27, v16, v17
	v_pk_mul_f32 v[0:1], v[4:5], v[0:1]
	v_add_u32_e32 v16, 0xb0, v154
	v_cvt_pk_bf16_f32 v10, v0, v1
	v_pk_mul_f32 v[0:1], v[6:7], v[12:13]
	v_mad_i64_i32 v[156:157], s[22:23], v154, s44, v[146:147]
	v_lshlrev_b64 v[144:145], 1, v[144:145]
	v_mad_i64_i32 v[112:113], s[22:23], v112, s44, v[146:147]
	v_mad_i64_i32 v[96:97], s[22:23], v96, s44, v[146:147]
	v_mad_i64_i32 v[80:81], s[22:23], v80, s44, v[146:147]
	v_mad_i64_i32 v[64:65], s[22:23], v64, s44, v[146:147]
	v_mad_i64_i32 v[48:49], s[22:23], v48, s44, v[146:147]
	v_mad_i64_i32 v[32:33], s[22:23], v32, s44, v[146:147]
	v_mad_i64_i32 v[16:17], s[22:23], v16, s44, v[146:147]
	v_pk_mul_f32 v[0:1], v[0:1], v[2:3]
	v_lshl_add_u64 v[156:157], v[156:157], 0, v[144:145]
	v_lshl_add_u64 v[112:113], v[112:113], 0, v[144:145]
	v_lshl_add_u64 v[96:97], v[96:97], 0, v[144:145]
	v_lshl_add_u64 v[80:81], v[80:81], 0, v[144:145]
	v_lshl_add_u64 v[64:65], v[64:65], 0, v[144:145]
	v_lshl_add_u64 v[48:49], v[48:49], 0, v[144:145]
	v_lshl_add_u64 v[32:33], v[32:33], 0, v[144:145]
	v_lshl_add_u64 v[16:17], v[16:17], 0, v[144:145]
	v_cvt_pk_bf16_f32 v11, v0, v1
	s_andn2_b64 vcc, exec, s[6:7]
	s_mov_b64 s[6:7], -1
	global_store_dwordx4 v[156:157], v[120:123], off
	global_store_dwordx4 v[112:113], v[104:107], off
	global_store_dwordx4 v[96:97], v[88:91], off
	global_store_dwordx4 v[80:81], v[72:75], off
	global_store_dwordx4 v[64:65], v[56:59], off
	global_store_dwordx4 v[48:49], v[40:43], off
	global_store_dwordx4 v[32:33], v[24:27], off
	global_store_dwordx4 v[16:17], v[8:11], off
	s_cbranch_vccnz .LBB0_1307
	s_andn2_b64 vcc, exec, s[0:1]
	s_cbranch_vccnz .LBB0_1306
	s_barrier
	s_branch .LBB0_1306

; __device__ __forceinline__ int lane_now() { int l; asm volatile("v_mbcnt_lo_u32_b32 %0, -1, 0\n\tv_mbcnt_hi_u32_b32 %0, -1, %0" : "=v"(l)); return l; }
; #define PG8_STAGE(bufoff, gbase, voff) do { _Pragma("unroll") for (int _i = 0; _i < 2; ++_i) \
;         __builtin_amdgcn_global_load_lds((const unsigned*)((const char*)(gbase) + (voff)[_i]), (PG8_LAS unsigned*)(lds + (bufoff) + ldsw + _i * 8192), 16, 0, 0); } while (0)
; #define PG8_WAIT_V(n) asm volatile("s_waitcnt vmcnt(" #n ")" ::: "memory")
; #define PG8_BAR __builtin_amdgcn_s_barrier()
; #define lane (lane_now())
; template <class Epi, class Sched, bool ALIGN_EPI = false, bool SP2 = false>
; __device__ __forceinline__ void gemm_phase(PG8_LAS unsigned char* lds, const Gemm g, const Sched& S, const Epi& E, const int wid) {
;     const int lane = lane_now(), tid = wid * 64 + lane, wr = wid >> 2, wc = wid & 3, fr = lane & 15, fq = lane >> 4;
;     const int K = g.K, nt = K / BK;
;     unsigned voffA[2], voffB[2];
; #pragma unroll
;     for (int i = 0; i < 2; ++i) { int R, C; stage_rc(tid * 16 + i * 8192, R, C); const int Rb = Epi::PERM ? ((R & ~31) + perm32(R & 31)) : R;
;         voffA[i] = (unsigned)(R * K + C) * 2u; voffB[i] = (unsigned)(Rb * K + C) * 2u; }
;     const size_t kstep = (size_t)(BK * 2);
;     const size_t hstep = (size_t)HALF * K * 2;
;     const size_t tstep = 2 * hstep;
;     const unsigned ldsw = (unsigned)wid * 1024u;
;     const int aoff = lds_byte(wr * 64 + fr, fq * 8), boff = lds_byte(wc * 32 + fr, fq * 8);
;     ...
;     const char* cA = (const char*)g.A + (size_t)cur.pm * tstep; const char* cB = (const char*)g.Bt + (size_t)cur.pn * tstep;
;     S.a_ready(cur);
;     if constexpr (SP2) {
;         PG8_STAGE(PG8_SB(0, 0), cB, voffB); PG8_STAGE(PG8_SB(0, 1), cB + hstep, voffB); PG8_STAGE(PG8_SA(0, 0), cA, voffA); PG8_STAGE(PG8_SA(0, 1), cA + hstep, voffA);
;         if (wr == 1) PG8_BAR;
;         PG8_WAIT_V(2); PG8_BAR;
;         PG8_STAGE(PG8_SB(1, 0), cB + kstep, voffB); PG8_STAGE(PG8_SA(1, 0), cA + kstep, voffA); PG8_STAGE(PG8_SB(1, 1), cB + hstep + kstep, voffB);
.LBB0_1377:
	v_lshl_add_u32 v0, v8, 4, s33
	v_ashrrev_i32_e32 v1, 31, v0
	v_lshrrev_b32_e32 v1, 22, v1
	v_add_u32_e32 v1, v0, v1
	v_ashrrev_i32_e32 v9, 10, v1
	v_mul_i32_i24_e32 v1, 0x400, v9
	v_sub_u32_e32 v1, v0, v1
	v_lshrrev_b32_e32 v2, 4, v1
	v_bitop3_b32 v1, v2, v1, 32 bitop3:0x6c
	v_ashrrev_i32_e32 v3, 31, v1
	v_lshrrev_b32_e32 v3, 26, v3
	v_lshlrev_b32_e32 v2, 3, v9
	v_add_u32_e32 v3, v1, v3
	v_and_b32_e32 v2, -16, v2
	v_ashrrev_i32_e32 v11, 6, v3
	v_and_b32_e32 v3, 0xc0, v3
	v_add_u32_e32 v2, v11, v2
	v_lshlrev_b32_e32 v4, 5, v9
	v_sub_u32_e32 v1, v1, v3
	v_mov_b32_e32 v3, 1
	v_and_b32_e32 v10, 32, v4
	v_ashrrev_i16_sdwa v1, v3, sext(v1) dst_sel:DWORD dst_unused:UNUSED_PAD src0_sel:DWORD src1_sel:BYTE_0
	v_lshlrev_b32_e32 v4, 1, v2
	v_lshrrev_b32_e32 v5, 2, v2
	v_and_b32_e32 v6, 3, v11
	s_mov_b32 s3, 0xffffe0
	v_bfe_i32 v12, v1, 0, 16
	v_and_b32_e32 v4, 24, v4
	v_and_b32_e32 v5, 4, v5
	v_and_or_b32 v6, v2, s3, v6
	s_movk_i32 s0, 0xb00
	v_add_u32_e32 v1, v10, v12
	v_or3_b32 v4, v6, v5, v4
	v_mul_lo_u32 v2, v2, s0
	v_add_lshl_u32 v128, v1, v2, 1
	v_mul_u32_u24_e32 v2, 0xb00, v4
	v_add_u32_e32 v0, 0x2000, v0
	v_add_lshl_u32 v130, v2, v1, 1
	v_ashrrev_i32_e32 v1, 31, v0
	v_lshrrev_b32_e32 v1, 22, v1
	v_add_u32_e32 v1, v0, v1
	v_ashrrev_i32_e32 v13, 10, v1
	v_mul_i32_i24_e32 v1, 0x400, v13
	v_sub_u32_e32 v0, v0, v1
	v_lshrrev_b32_e32 v1, 4, v0
	v_bitop3_b32 v0, v1, v0, 32 bitop3:0x6c
	s_add_u32 s29, s92, 0x1c80000
	v_ashrrev_i32_e32 v2, 31, v0
	s_addc_u32 s30, s93, 0
	v_lshrrev_b32_e32 v2, 26, v2
	s_add_i32 s1, s2, s1
	v_lshlrev_b32_e32 v1, 3, v13
	v_add_u32_e32 v2, v0, v2
	s_ashr_i32 s2, s1, 31
	v_and_b32_e32 v1, -16, v1
	v_ashrrev_i32_e32 v14, 6, v2
	v_lshlrev_b32_e32 v4, 5, v13
	s_lshr_b32 s2, s2, 28
	v_add_u32_e32 v1, v14, v1
	v_and_b32_e32 v15, 32, v4
	v_and_b32_e32 v4, 3, v14
	s_add_i32 s2, s1, s2
	v_and_or_b32 v4, v1, s3, v4
	s_ashr_i32 s3, s2, 4
	s_and_b32 s2, s2, 0xfff0
	s_sub_i32 s2, s1, s2
	s_bfe_i32 s1, s2, 0x80000
	s_bfe_u32 s1, s1, 0x2000d
	s_add_i32 s4, s2, s1
	v_and_b32_e32 v2, 0xffc0, v2
	s_bfe_i32 s1, s4, 0x80000
	s_and_b32 s4, s4, 0xfc
	v_sub_u32_e32 v0, v0, v2
	s_sub_i32 s2, s2, s4
	v_lshrrev_b16_e32 v2, 7, v0
	s_lshl_b32 s3, s3, 2
	s_sext_i32_i16 s5, s1
	s_sext_i32_i8 s2, s2
	v_and_b32_e32 v2, 1, v2
	s_add_i32 s47, s3, s2
	s_ashr_i32 s2, s5, 2
	v_add_u16_e32 v0, v0, v2
	s_lshr_b32 s1, s5, 2
	s_mul_hi_i32 s3, s2, 0x160000
	s_mul_i32 s2, s2, 0x160000
	v_ashrrev_i16_sdwa v0, v3, sext(v0) dst_sel:DWORD dst_unused:UNUSED_PAD src0_sel:DWORD src1_sel:BYTE_0
	v_lshlrev_b32_e32 v2, 1, v1
	v_lshrrev_b32_e32 v3, 2, v1
	s_add_u32 s22, s29, s2
	v_bfe_i32 v16, v0, 0, 16
	v_and_b32_e32 v2, 24, v2
	v_and_b32_e32 v3, 4, v3
	s_addc_u32 s23, s30, s3
	s_add_i32 s31, s33, 0
	v_add_u32_e32 v0, v15, v16
	v_or3_b32 v2, v4, v3, v2
	v_mul_lo_u32 v1, v1, s0
	s_add_i32 m0, s31, 0x10000
	v_add_lshl_u32 v132, v0, v1, 1
	v_mul_u32_u24_e32 v1, 0xb00, v2
	global_load_lds_dwordx4 v130, s[22:23]
	s_add_i32 m0, s31, 0x12000
	v_add_lshl_u32 v134, v1, v0, 1
	s_add_u32 s2, s22, 0xb0000
	global_load_lds_dwordx4 v134, s[22:23]
	s_addc_u32 s3, s23, 0
	s_add_i32 m0, s31, 0x14000
	s_mul_i32 s6, s47, 0x160000
	global_load_lds_dwordx4 v130, s[2:3]
	s_add_i32 m0, s31, 0x16000
	s_mul_hi_i32 s4, s47, 0x160000
	s_add_u32 s20, s96, s6
	s_addc_u32 s21, s97, s4
	s_lshr_b32 s98, s47, 1
	s_and_b32 s99, s98, 7
	s_lshl_b32 s99, s99, 1
	s_bfe_u32 s100, s98, 0x10003
	s_or_b32 s99, s99, s100
	s_and_b32 s100, s98, 0x30
	s_or_b32 s99, s99, s100
	s_mul_i32 s99, s99, 0x300000
	s_mul_i32 s98, s98, 0x2c0000
	s_add_u32 s99, s99, 0xd000000
	s_sub_u32 s99, s99, s98
	s_add_u32 s20, s20, s99
	s_addc_u32 s21, s21, 0
	s_add_i32 s34, s31, 0x2000
	global_load_lds_dwordx4 v134, s[2:3]
	s_mov_b32 m0, s31
	s_add_u32 s2, s20, 0xb0000
	global_load_lds_dwordx4 v128, s[20:21]
	s_mov_b32 m0, s34
	s_addc_u32 s3, s21, 0
	s_add_i32 s35, s31, 0x4000
	global_load_lds_dwordx4 v132, s[20:21]
	s_mov_b32 m0, s35
	s_add_i32 s36, s31, 0x6000
	global_load_lds_dwordx4 v128, s[2:3]
	s_mov_b32 m0, s36
	v_mov_b32_e32 v131, 0
	global_load_lds_dwordx4 v132, s[2:3]
	v_readlane_b32 s4, v244, 18
	v_mov_b32_e32 v135, v131
	v_mov_b32_e32 v129, v131
	v_mov_b32_e32 v133, v131
	s_cmp_eq_u32 s4, 1
	s_mov_b32 s37, 0
	v_lshl_add_u64 v[4:5], s[22:23], 0, v[130:131]
	v_lshl_add_u64 v[2:3], s[22:23], 0, v[134:135]
	s_mov_b64 s[2:3], 0xb0000
	v_lshl_add_u64 v[0:1], s[20:21], 0, v[128:129]
	s_cselect_b64 s[6:7], -1, 0
	s_cmp_lg_u32 s4, 1
	v_lshl_add_u64 v[6:7], s[20:21], 0, v[132:133]
	s_cbranch_scc1 .LBB0_1379
	s_barrier

; template <class Epi, class Sched, bool ALIGN_EPI = false, bool SP2 = false>
; __device__ __forceinline__ void gemm_phase(PG8_LAS unsigned char* lds, const Gemm g, const Sched& S, const Epi& E, const int wid) {
;     ...
;         const bool has_next = S.next(ui + 1, nxt);
;         const char* nA = has_next ? (const char*)g.A + (size_t)nxt.pm * tstep : cA; const char* nB = has_next ? (const char*)g.Bt + (size_t)nxt.pn * tstep : cB;
.LBB0_1388:
	s_nop 0
	v_cndmask_b32_e64 v0, 0, 1, s[4:5]
	v_cmp_ne_u32_e64 s[0:1], 1, v0
	s_andn2_b64 vcc, exec, s[4:5]
	s_mov_b64 s[4:5], s[20:21]
	s_cbranch_vccnz .LBB0_1390
	s_mul_i32 s4, s46, 0x160000
	s_mul_hi_i32 s5, s46, 0x160000
	s_add_u32 s4, s96, s4
	s_addc_u32 s5, s97, s5
	s_lshr_b32 s98, s46, 1
	s_and_b32 s99, s98, 7
	s_lshl_b32 s99, s99, 1
	s_bfe_u32 s100, s98, 0x10003
	s_or_b32 s99, s99, s100
	s_and_b32 s100, s98, 0x30
	s_or_b32 s99, s99, s100
	s_mul_i32 s99, s99, 0x300000
	s_mul_i32 s98, s98, 0x2c0000
	s_add_u32 s99, s99, 0xd000000
	s_sub_u32 s99, s99, s98
	s_add_u32 s4, s4, s99
	s_addc_u32 s5, s5, 0
